# NSA: heavy/light query-tile pairing per CU, static softmax reference (QK-norm bound), hand-pipelined interior-tile path; plus RES/FIN epilogue prefetch
# speedup vs baseline: 1.0534x; 1.0378x over previous
.LBB0_303:
	s_and_b64 vcc, exec, s[40:41]
	s_cbranch_vccz .LBB0_298
	s_sub_i32 s45, s21, 0x100
	s_lshr_b32 s45, s45, 3
	s_sub_i32 s45, 63, s45
	s_lshl_b32 s45, s45, 3
	s_and_b32 s46, s21, 7
	s_or_b32 s45, s45, s46
	s_cmpk_lt_i32 s21, 0x100
	s_cselect_b32 s44, s21, s45
	v_mov_b32_e32 v118, v131
	s_lshl_b32 s22, s44, 2
	s_load_dwordx2 s[40:41], s[12:13], 0x170
	s_andn2_b32 s22, s22, 31
	v_ashrrev_i32_e32 v120, 3, v118
	s_sub_i32 s23, 0x7e0, s22
	v_and_b32_e32 v126, -8, v120
	v_bfe_u32 v121, v118, 2, 3
	v_add_u32_e32 v0, s23, v126
	s_lshl_b32 s24, s44, 10
	s_and_b32 s79, s44, 1
	v_and_b32_e32 v127, 3, v118
	v_or_b32_e32 v117, v0, v121
	s_and_b32 s24, s24, 0x1800
	v_lshl_or_b32 v129, s79, 2, v127
	v_add_u32_e32 v114, s24, v117
	s_waitcnt lgkmcnt(0)
	v_mov_b64_e32 v[2:3], s[40:41]
	v_bfe_u32 v135, v118, 5, 1
	v_mad_i64_i32 v[124:125], s[40:41], v114, s33, v[2:3]
	v_lshlrev_b32_e32 v0, 8, v129
	v_lshl_add_u64 v[2:3], v[124:125], 0, v[0:1]
	v_lshlrev_b32_e32 v122, 4, v135
	v_mov_b32_e32 v123, v1
	v_lshl_add_u64 v[2:3], v[2:3], 0, v[122:123]
	s_load_dwordx4 s[28:31], s[12:13], 0x198
	global_load_dwordx4 v[82:85], v[2:3], off
	global_load_dwordx4 v[86:89], v[2:3], off offset:32
	global_load_dwordx4 v[90:93], v[2:3], off offset:64
	global_load_dwordx4 v[94:97], v[2:3], off offset:96
	global_load_dwordx4 v[98:101], v[2:3], off offset:128
	global_load_dwordx4 v[102:105], v[2:3], off offset:160
	global_load_dwordx4 v[106:109], v[2:3], off offset:192
	global_load_dwordx4 v[110:113], v[2:3], off offset:224
	s_lshl_b32 s25, s44, 7
	s_and_b32 s82, s25, 0x380
	v_add_u32_e32 v0, 1, v129
	s_lshl_b32 s25, s82, 8
	v_cvt_f32_ubyte0_e32 v0, v0
	s_waitcnt lgkmcnt(0)
	s_add_u32 s28, s28, s25
	v_exp_f32_e64 v5, -v0
	s_addc_u32 s29, s29, 0
	s_add_u32 s30, s30, s25
	v_lshlrev_b32_e32 v0, 4, v118
	s_addc_u32 s31, s31, 0
	v_and_b32_e32 v0, 0xf0, v0
	v_and_b32_e32 v173, 31, v118
	v_ashrrev_i32_e32 v115, 31, v114
	v_lshlrev_b32_e32 v116, 7, v129
	v_lshlrev_b32_e32 v18, 3, v135
	v_lshlrev_b32_e32 v171, 3, v118
	v_lshl_add_u64 v[2:3], s[28:29], 0, v[0:1]
	v_add_u32_e32 v4, 16, v0
	v_lshl_add_u64 v[6:7], s[30:31], 0, v[0:1]
	s_mov_b32 s25, 0
	s_barrier
.LBB0_305:
	v_add_u32_e32 v0, s25, v118
	v_ashrrev_i32_e32 v19, 4, v0
	v_add_u32_e32 v0, 0x100, v0
	v_ashrrev_i32_e32 v0, 4, v0
	v_lshlrev_b32_e32 v8, 7, v19
	v_lshlrev_b32_e32 v10, 7, v0
	v_ashrrev_i32_e32 v9, 31, v8
	v_ashrrev_i32_e32 v11, 31, v10
	v_lshlrev_b64 v[8:9], 1, v[8:9]
	v_lshlrev_b64 v[16:17], 1, v[10:11]
	v_lshl_add_u64 v[12:13], v[2:3], 0, v[8:9]
	v_lshl_add_u64 v[14:15], v[6:7], 0, v[8:9]
	v_lshl_add_u64 v[20:21], v[2:3], 0, v[16:17]
	global_load_dwordx4 v[8:11], v[12:13], off
	s_nop 0
	global_load_dwordx4 v[12:15], v[14:15], off
	v_lshl_add_u64 v[16:17], v[6:7], 0, v[16:17]
	global_load_dwordx4 v[20:23], v[20:21], off
	s_nop 0
	global_load_dwordx4 v[24:27], v[16:17], off
	s_addk_i32 s25, 0x200
	s_cmpk_eq_i32 s25, 0x800
	v_mad_u64_u32 v[16:17], s[28:29], v19, s36, v[4:5]
	v_mad_u64_u32 v[28:29], s[28:29], v0, s36, v[4:5]
	s_waitcnt vmcnt(3)
	ds_write_b128 v16, v[8:11]
	s_waitcnt vmcnt(2)
	ds_write_b128 v16, v[12:15] offset:34816
	s_waitcnt vmcnt(1)
	ds_write_b128 v28, v[20:23]
	s_waitcnt vmcnt(0)
	ds_write_b128 v28, v[24:27] offset:34816
	s_cbranch_scc0 .LBB0_305
	v_cmp_gt_i32_e32 vcc, 32, v118
	s_and_saveexec_b64 s[40:41], vcc
	v_lshl_add_u32 v0, v118, 2, 16
	v_add_u32_e32 v0, 0x11f80, v0
	ds_write_b32 v0, v1
	s_or_b64 exec, exec, s[40:41]
	v_and_b32_e32 v3, 64, v160
	v_xor_b32_e32 v2, 32, v160
	v_add_u32_e32 v128, 64, v3
	v_cmp_lt_i32_e32 vcc, v2, v128
	s_lshl_b32 s28, s44, 2
	s_and_b32 s28, s28, 0xffffffe0
	v_lshlrev_b32_e32 v0, 6, v135
	v_cndmask_b32_e32 v2, v160, v2, vcc
	v_lshlrev_b32_e32 v172, 2, v2
	v_add_u32_e32 v2, v121, v126
	v_subrev_u32_e32 v2, s28, v2
	v_sub_u32_e32 v2, v2, v0
	v_add_u32_e32 v19, 0x7e0, v2
	v_mul_u32_u24_e32 v2, 0x110, v173
	v_mul_f32_e32 v119, 0x3fb8aa3b, v5
	s_mov_b32 s25, 0
	v_add3_u32 v20, v2, v122, 16
	v_mov_b32_e32 v139, 0xf149f2ca
	v_mov_b32_e32 v22, 0
	s_movk_i32 s28, 0x9e
	s_movk_i32 s29, 0xae
	s_movk_i32 s30, 0xbe
	s_movk_i32 s31, 0xce
	s_movk_i32 s34, 0x11e
	s_movk_i32 s94, 0x12e
	s_movk_i32 s95, 0x13e
	s_movk_i32 s73, 0x14e
	s_movk_i32 s89, 0x1ae
	s_movk_i32 s1, 0x1be
	s_waitcnt lgkmcnt(0)
	s_barrier

.LBB0_312:
	s_or_b64 exec, exec, s[42:43]
	v_add_u32_e32 v38, s23, v120
	v_ashrrev_i32_e32 v40, 6, v38
	v_lshl_add_u32 v46, v120, 7, 16
	v_add_u32_e32 v41, -1, v40
	s_waitcnt lgkmcnt(0)
	s_barrier
	ds_read_b128 v[6:9], v46
	ds_read_b128 v[2:5], v46 offset:16
	ds_read_b128 v[10:13], v46 offset:32
	ds_read_b128 v[14:17], v46 offset:48
	v_cmp_gt_u32_e32 vcc, 2, v41
	v_lshl_add_u64 v[124:125], s[40:41], 0, v[0:1]
	s_movk_i32 s25, 0x80
	v_cndmask_b32_e32 v0, 0, v132, vcc
	s_waitcnt lgkmcnt(3)
	v_add_f32_e32 v0, v0, v7
	v_cmp_lt_i32_e32 vcc, 63, v38
	v_and_b32_e32 v7, 0xffffff80, v38
	s_movk_i32 s0, 0x7f
	v_cndmask_b32_e32 v30, v162, v0, vcc
	v_cmp_eq_u32_e32 vcc, s25, v7
	s_movk_i32 s25, 0xbf
	ds_read_b128 v[22:25], v46 offset:80
	v_cndmask_b32_e32 v0, 0, v132, vcc
	v_add_f32_e32 v0, v0, v8
	v_cmp_lt_i32_e32 vcc, s0, v38
	s_movk_i32 s0, 0x480
	ds_read_b128 v[42:45], v46 offset:112
	v_cndmask_b32_e32 v31, v162, v0, vcc
	v_add_u32_e32 v0, -3, v40
	v_cmp_gt_u32_e32 vcc, 2, v0
	v_readlane_b32 s1, v209, 22
	s_mulk_i32 s24, 0x2500
	v_cndmask_b32_e32 v0, 0, v132, vcc
	v_add_f32_e32 v0, v0, v9
	v_cmp_lt_i32_e32 vcc, s25, v38
	s_movk_i32 s25, 0x100
	v_mov_b32_e32 v137, v1
	v_cndmask_b32_e32 v32, v162, v0, vcc
	v_cmp_eq_u32_e32 vcc, s25, v7
	s_movk_i32 s25, 0xff
	v_mov_b32_e32 v143, v1
	v_cndmask_b32_e32 v0, 0, v132, vcc
	s_waitcnt lgkmcnt(4)
	v_add_f32_e32 v0, v0, v2
	v_cmp_lt_i32_e32 vcc, s25, v38
	s_movk_i32 s25, 0x13f
	s_nop 0
	v_cndmask_b32_e32 v33, v162, v0, vcc
	v_add_u32_e32 v0, -5, v40
	v_cmp_gt_u32_e32 vcc, 2, v0
	s_nop 1
	v_cndmask_b32_e32 v0, 0, v132, vcc
	v_add_f32_e32 v0, v0, v3
	v_cmp_lt_i32_e32 vcc, s25, v38
	s_movk_i32 s25, 0x180
	s_nop 0
	v_cndmask_b32_e32 v35, v162, v0, vcc
	v_cmp_eq_u32_e32 vcc, s25, v7
	s_movk_i32 s25, 0x17f
	s_nop 0
	v_cndmask_b32_e32 v0, 0, v132, vcc
	v_add_f32_e32 v0, v0, v4
	v_cmp_lt_i32_e32 vcc, s25, v38
	s_movk_i32 s25, 0x1bf
	s_nop 0
	v_cndmask_b32_e32 v34, v162, v0, vcc
	v_add_u32_e32 v0, -7, v40
	v_cmp_gt_u32_e32 vcc, 2, v0
	s_nop 1
	v_cndmask_b32_e32 v0, 0, v132, vcc
	v_add_f32_e32 v0, v0, v5
	v_cmp_lt_i32_e32 vcc, s25, v38
	s_movk_i32 s25, 0x200
	s_nop 0
	v_cndmask_b32_e32 v36, v162, v0, vcc
	v_cmp_eq_u32_e32 vcc, s25, v7
	s_movk_i32 s25, 0x1ff
	s_nop 0
	v_cndmask_b32_e32 v0, 0, v132, vcc
	s_waitcnt lgkmcnt(3)
	v_add_f32_e32 v0, v0, v10
	v_cmp_lt_i32_e32 vcc, s25, v38
	s_movk_i32 s25, 0x23f
	s_nop 0
	v_cndmask_b32_e32 v37, v162, v0, vcc
	v_add_u32_e32 v0, -9, v40
	v_cmp_gt_u32_e32 vcc, 2, v0
	s_nop 1
	v_cndmask_b32_e32 v0, 0, v132, vcc
	v_add_f32_e32 v0, v0, v11
	v_cmp_lt_i32_e32 vcc, s25, v38
	s_movk_i32 s25, 0x280
	s_nop 0
	v_cndmask_b32_e32 v0, v162, v0, vcc
	v_cmp_eq_u32_e32 vcc, s25, v7
	s_movk_i32 s25, 0x27f
	s_nop 0
	v_cndmask_b32_e32 v2, 0, v132, vcc
	v_add_f32_e32 v2, v2, v12
	v_cmp_lt_i32_e32 vcc, s25, v38
	s_movk_i32 s25, 0x2bf
	s_nop 0
	v_cndmask_b32_e32 v8, v162, v2, vcc
	v_add_u32_e32 v2, -11, v40
	v_cmp_gt_u32_e32 vcc, 2, v2
	s_nop 1
	v_cndmask_b32_e32 v2, 0, v132, vcc
	v_add_f32_e32 v2, v2, v13
	v_cmp_lt_i32_e32 vcc, s25, v38
	s_movk_i32 s25, 0x300
	s_nop 0
	v_cndmask_b32_e32 v9, v162, v2, vcc
	v_cmp_eq_u32_e32 vcc, s25, v7
	s_movk_i32 s25, 0x2ff
	s_nop 0
	v_cndmask_b32_e32 v2, 0, v132, vcc
	s_waitcnt lgkmcnt(2)
	v_add_f32_e32 v2, v2, v14
	v_cmp_lt_i32_e32 vcc, s25, v38
	s_movk_i32 s25, 0x33f
	s_nop 0
	v_cndmask_b32_e32 v10, v162, v2, vcc
	v_add_u32_e32 v2, -13, v40
	v_cmp_gt_u32_e32 vcc, 2, v2
	s_nop 1
	v_cndmask_b32_e32 v2, 0, v132, vcc
	v_add_f32_e32 v2, v2, v15
	v_cmp_lt_i32_e32 vcc, s25, v38
	s_movk_i32 s25, 0x380
	s_nop 0
	v_cndmask_b32_e32 v11, v162, v2, vcc
	v_cmp_eq_u32_e32 vcc, s25, v7
	s_movk_i32 s25, 0x37f
	s_nop 0
	v_cndmask_b32_e32 v2, 0, v132, vcc
	v_add_f32_e32 v2, v2, v16
	v_cmp_lt_i32_e32 vcc, s25, v38
	s_movk_i32 s25, 0x3bf
	s_nop 0
	v_cndmask_b32_e32 v12, v162, v2, vcc
	v_add_u32_e32 v2, -15, v40
	v_cmp_gt_u32_e32 vcc, 2, v2
	s_nop 1
	v_cndmask_b32_e32 v2, 0, v132, vcc
	v_add_f32_e32 v13, v2, v17
	ds_read_b128 v[2:5], v46 offset:64
	v_cmp_lt_i32_e32 vcc, s25, v38
	s_movk_i32 s25, 0x400
	s_nop 0
	v_cndmask_b32_e32 v13, v162, v13, vcc
	v_cmp_eq_u32_e32 vcc, s25, v7
	s_movk_i32 s25, 0x3ff
	s_nop 0
	v_cndmask_b32_e32 v14, 0, v132, vcc
	s_waitcnt lgkmcnt(0)
	v_add_f32_e32 v2, v14, v2
	v_cmp_lt_i32_e32 vcc, s25, v38
	s_movk_i32 s25, 0x43f
	s_nop 0
	v_cndmask_b32_e32 v14, v162, v2, vcc
	v_subrev_u32_e32 v2, 17, v40
	v_cmp_gt_u32_e32 vcc, 2, v2
	s_nop 1
	v_cndmask_b32_e32 v2, 0, v132, vcc
	v_add_f32_e32 v2, v2, v3
	v_cmp_lt_i32_e32 vcc, s25, v38
	s_movk_i32 s25, 0x47f
	s_nop 0
	v_cndmask_b32_e32 v21, v162, v2, vcc
	v_cmp_eq_u32_e32 vcc, s0, v7
	s_movk_i32 s0, 0x500
	s_nop 0
	v_cndmask_b32_e32 v2, 0, v132, vcc
	v_add_f32_e32 v2, v2, v4
	v_cmp_lt_i32_e32 vcc, s25, v38
	s_movk_i32 s25, 0x4bf
	s_nop 0
	v_cndmask_b32_e32 v19, v162, v2, vcc
	v_subrev_u32_e32 v2, 19, v40
	v_cmp_gt_u32_e32 vcc, 2, v2
	s_nop 1
	v_cndmask_b32_e32 v2, 0, v132, vcc
	v_add_f32_e32 v2, v2, v5
	v_cmp_lt_i32_e32 vcc, s25, v38
	s_movk_i32 s25, 0x4ff
	s_nop 0
	v_cndmask_b32_e32 v15, v162, v2, vcc
	v_cmp_eq_u32_e32 vcc, s0, v7
	s_nop 1
	v_cndmask_b32_e32 v2, 0, v132, vcc
	v_add_f32_e32 v2, v2, v22
	v_cmp_lt_i32_e32 vcc, s25, v38
	s_movk_i32 s25, 0x53f
	s_nop 0
	v_cndmask_b32_e32 v16, v162, v2, vcc
	v_subrev_u32_e32 v2, 21, v40
	v_cmp_gt_u32_e32 vcc, 2, v2
	s_nop 1
	v_cndmask_b32_e32 v2, 0, v132, vcc
	v_add_f32_e32 v2, v2, v23
	v_cmp_lt_i32_e32 vcc, s25, v38
	s_movk_i32 s25, 0x580
	s_nop 0
	v_cndmask_b32_e32 v17, v162, v2, vcc
	v_cmp_eq_u32_e32 vcc, s25, v7
	s_movk_i32 s25, 0x57f
	s_nop 0
	v_cndmask_b32_e32 v2, 0, v132, vcc
	v_add_f32_e32 v2, v2, v24
	v_cmp_lt_i32_e32 vcc, s25, v38
	s_movk_i32 s25, 0x5bf
	s_nop 0
	v_cndmask_b32_e32 v18, v162, v2, vcc
	v_subrev_u32_e32 v2, 23, v40
	v_cmp_gt_u32_e32 vcc, 2, v2
	s_nop 1
	v_cndmask_b32_e32 v2, 0, v132, vcc
	v_add_f32_e32 v20, v2, v25
	ds_read_b128 v[2:5], v46 offset:96
	v_cmp_lt_i32_e32 vcc, s25, v38
	s_movk_i32 s25, 0x600
	s_nop 0
	v_cndmask_b32_e32 v20, v162, v20, vcc
	v_cmp_eq_u32_e32 vcc, s25, v7
	s_movk_i32 s25, 0x5ff
	s_nop 0
	v_cndmask_b32_e32 v22, 0, v132, vcc
	s_waitcnt lgkmcnt(0)
	v_add_f32_e32 v2, v22, v2
	v_cmp_lt_i32_e32 vcc, s25, v38
	s_movk_i32 s25, 0x63f
	v_lshlrev_b32_e32 v22, 2, v118
	v_cndmask_b32_e32 v23, v162, v2, vcc
	v_subrev_u32_e32 v2, 25, v40
	v_cmp_gt_u32_e32 vcc, 2, v2
	s_nop 1
	v_cndmask_b32_e32 v2, 0, v132, vcc
	v_add_f32_e32 v2, v2, v3
	v_cmp_lt_i32_e32 vcc, s25, v38
	s_movk_i32 s25, 0x680
	s_nop 0
	v_cndmask_b32_e32 v25, v162, v2, vcc
	v_cmp_eq_u32_e32 vcc, s25, v7
	s_movk_i32 s25, 0x67f
	s_nop 0
	v_cndmask_b32_e32 v2, 0, v132, vcc
	v_add_f32_e32 v2, v2, v4
	v_cmp_lt_i32_e32 vcc, s25, v38
	s_movk_i32 s25, 0x6bf
	s_nop 0
	v_cndmask_b32_e32 v26, v162, v2, vcc
	v_subrev_u32_e32 v2, 27, v40
	v_cmp_gt_u32_e32 vcc, 2, v2
	s_nop 1
	v_cndmask_b32_e32 v2, 0, v132, vcc
	v_add_f32_e32 v2, v2, v5
	v_cmp_lt_i32_e32 vcc, s25, v38
	s_movk_i32 s25, 0x700
	s_nop 0
	v_cndmask_b32_e32 v27, v162, v2, vcc
	v_cmp_eq_u32_e32 vcc, s25, v7
	s_movk_i32 s25, 0x6ff
	s_nop 0
	v_cndmask_b32_e32 v2, 0, v132, vcc
	v_add_f32_e32 v2, v2, v42
	v_cmp_lt_i32_e32 vcc, s25, v38
	s_movk_i32 s25, 0x73f
	v_and_b32_e32 v42, 28, v22
	v_cndmask_b32_e32 v24, v162, v2, vcc
	v_subrev_u32_e32 v2, 29, v40
	v_cmp_gt_u32_e32 vcc, 2, v2
	v_cmp_eq_u32_e64 s[40:41], v42, v40
	v_cmp_lt_u32_e64 s[46:47], 4, v42
	v_cndmask_b32_e32 v2, 0, v132, vcc
	v_add_f32_e32 v2, v2, v43
	v_cmp_lt_i32_e32 vcc, s25, v38
	s_movk_i32 s25, 0x780
	v_cmp_lt_u32_e64 s[50:51], 6, v42
	v_cndmask_b32_e32 v29, v162, v2, vcc
	v_cmp_eq_u32_e32 vcc, s25, v7
	s_movk_i32 s25, 0x77f
	v_lshlrev_b32_e32 v7, 6, v42
	v_cndmask_b32_e32 v2, 0, v132, vcc
	v_add_f32_e32 v2, v2, v44
	v_cmp_lt_i32_e32 vcc, s25, v38
	s_movk_i32 s25, 0x7bf
	v_cmp_lt_u32_e64 s[54:55], 8, v42
	v_cndmask_b32_e32 v28, v162, v2, vcc
	v_subrev_u32_e32 v2, 31, v40
	v_cmp_gt_u32_e32 vcc, 2, v2
	s_nop 1
	v_cndmask_b32_e32 v2, 0, v132, vcc
	v_add_f32_e32 v2, v2, v45
	v_cmp_lt_i32_e32 vcc, s25, v38
	s_add_i32 s25, 16, 0x11f80
	s_nop 0
	v_cndmask_b32_e32 v39, v162, v2, vcc
	v_lshl_add_u32 v2, v42, 2, v46
	ds_read_b128 v[2:5], v2
	v_cmp_eq_u32_e32 vcc, 0, v42
	s_or_b64 s[28:29], vcc, s[40:41]
	v_cmp_eq_u32_e32 vcc, v42, v41
	s_or_b64 vcc, s[28:29], vcc
	s_nop 0
	v_cndmask_b32_e32 v43, 0, v132, vcc
	s_waitcnt lgkmcnt(0)
	v_add_f32_e32 v2, v43, v2
	v_cmp_le_i32_e32 vcc, v7, v38
	s_nop 1
	v_cndmask_b32_e32 v43, v162, v2, vcc
	v_cmp_ne_u32_e32 vcc, 0, v42
	v_cmp_eq_f32_e64 s[42:43], v30, v43
	v_cmp_gt_f32_e64 s[40:41], v30, v43
	s_and_b64 s[28:29], vcc, s[42:43]
	s_or_b64 s[28:29], s[40:41], s[28:29]
	v_cmp_eq_f32_e64 s[42:43], v31, v43
	v_cndmask_b32_e64 v44, 0, 1, s[28:29]
	v_cmp_gt_f32_e64 s[40:41], v31, v43
	s_and_b64 s[28:29], vcc, s[42:43]
	s_or_b64 s[28:29], s[40:41], s[28:29]
	v_cmp_eq_f32_e64 s[40:41], v32, v43
	v_cmp_eq_f32_e64 s[42:43], v33, v43
	v_cndmask_b32_e64 v45, 0, 1, s[28:29]
	s_and_b64 s[58:59], vcc, s[40:41]
	v_cmp_gt_f32_e64 s[40:41], v33, v43
	s_and_b64 s[28:29], s[42:43], s[46:47]
	s_or_b64 s[28:29], s[40:41], s[28:29]
	v_cmp_eq_f32_e64 s[40:41], v35, v43
	v_cmp_lt_u32_e64 s[42:43], 5, v42
	v_cmp_eq_f32_e64 s[48:49], v34, v43
	v_cndmask_b32_e64 v46, 0, 1, s[28:29]
	s_and_b64 s[60:61], s[40:41], s[42:43]
	v_cmp_gt_f32_e64 s[40:41], v34, v43
	s_and_b64 s[28:29], s[48:49], s[50:51]
	s_or_b64 s[28:29], s[40:41], s[28:29]
	v_cmp_eq_f32_e64 s[52:53], v37, v43
	v_cndmask_b32_e64 v47, 0, 1, s[28:29]
	s_and_b64 s[28:29], s[52:53], s[54:55]
	v_cmp_gt_f32_e64 s[54:55], v24, v43
	v_cmp_eq_f32_e64 s[50:51], v36, v43
	v_cmp_lt_u32_e64 s[40:41], 7, v42
	v_cndmask_b32_e64 v2, 0, 1, s[54:55]
	v_cmp_gt_f32_e64 s[54:55], v28, v43
	s_and_b64 s[62:63], s[50:51], s[40:41]
	v_cmp_gt_f32_e64 s[50:51], v37, v43
	v_cndmask_b32_e64 v7, 0, 1, s[54:55]
	v_cmp_gt_f32_e64 s[54:55], v29, v43
	s_or_b64 s[28:29], s[50:51], s[28:29]
	v_cndmask_b32_e64 v48, 0, 1, s[28:29]
	v_addc_co_u32_e64 v2, s[54:55], 0, v2, s[54:55]
	v_cmp_gt_f32_e64 s[54:55], v39, v43
	v_cmp_gt_f32_e64 s[44:45], v32, v43
	v_cmp_eq_f32_e64 s[52:53], v0, v43
	v_addc_co_u32_e64 v49, s[54:55], v2, v7, s[54:55]
	v_or_b32_e32 v2, 3, v42
	v_cmp_eq_u32_e64 s[54:55], v2, v40
	v_cmp_eq_u32_e64 s[56:57], v2, v41
	s_or_b64 s[54:55], s[54:55], s[56:57]
	v_cndmask_b32_e64 v133, 0, v132, s[54:55]
	v_mov_b32_e32 v7, v5
	v_pk_add_f32 v[6:7], v[132:133], v[6:7]
	v_cmp_lt_i32_e64 s[54:55], -1, v38
	s_or_b64 s[44:45], s[44:45], s[58:59]
	v_cmp_gt_f32_e64 s[46:47], v35, v43
	v_cndmask_b32_e64 v5, v162, v6, s[54:55]
	v_cmp_eq_f32_e64 s[56:57], v5, v43
	v_cmp_gt_f32_e64 s[54:55], v5, v43
	s_and_b64 s[28:29], vcc, s[56:57]
	s_or_b64 s[56:57], s[54:55], s[28:29]
	v_cmp_lt_u32_e64 s[54:55], 9, v42
	s_and_b64 s[28:29], s[52:53], s[54:55]
	v_addc_co_u32_e64 v6, s[52:53], v49, v44, s[56:57]
	v_addc_co_u32_e64 v6, s[44:45], v6, v45, s[44:45]
	s_or_b64 s[44:45], s[46:47], s[60:61]
	v_cmp_gt_f32_e64 s[48:49], v36, v43
	v_addc_co_u32_e64 v6, s[44:45], v6, v46, s[44:45]
	v_cmp_gt_f32_e64 s[50:51], v0, v43
	s_or_b64 s[44:45], s[48:49], s[62:63]
	v_addc_co_u32_e64 v6, s[44:45], v6, v47, s[44:45]
	s_or_b64 s[46:47], s[50:51], s[28:29]
	v_cmp_eq_f32_e64 s[48:49], v8, v43
	v_cmp_lt_u32_e64 s[50:51], 10, v42
	v_cmp_gt_f32_e64 s[44:45], v8, v43
	s_and_b64 s[28:29], s[48:49], s[50:51]
	s_or_b64 s[28:29], s[44:45], s[28:29]
	v_cmp_eq_f32_e64 s[50:51], v9, v43
	v_cmp_lt_u32_e64 s[44:45], 11, v42
	v_cmp_eq_f32_e64 s[52:53], v10, v43
	v_cmp_lt_u32_e64 s[56:57], 12, v42
	v_cndmask_b32_e64 v44, 0, 1, s[28:29]
	s_and_b64 s[28:29], s[50:51], s[44:45]
	v_cmp_gt_f32_e64 s[50:51], v10, v43
	s_and_b64 s[30:31], s[52:53], s[56:57]
	v_cmp_gt_f32_e64 s[48:49], v9, v43
	s_or_b64 s[30:31], s[50:51], s[30:31]
	v_cmp_eq_f32_e64 s[52:53], v11, v43
	v_cmp_lt_u32_e64 s[58:59], 13, v42
	v_cndmask_b32_e64 v45, 0, 1, s[30:31]
	s_and_b64 s[30:31], s[52:53], s[58:59]
	v_cmp_eq_f32_e64 s[52:53], v12, v43
	v_cmp_lt_u32_e64 s[56:57], 14, v42
	v_addc_co_u32_e64 v6, s[46:47], v6, v48, s[46:47]
	s_or_b64 s[48:49], s[48:49], s[28:29]
	v_cmp_gt_f32_e64 s[50:51], v11, v43
	s_and_b64 s[56:57], s[52:53], s[56:57]
	v_cmp_gt_f32_e64 s[52:53], v12, v43
	v_addc_co_u32_e64 v6, s[48:49], v6, v44, s[48:49]
	s_or_b64 s[52:53], s[52:53], s[56:57]
	v_cmp_eq_f32_e64 s[56:57], v13, v43
	v_cmp_lt_u32_e64 s[46:47], 15, v42
	s_or_b64 s[48:49], s[50:51], s[30:31]
	v_cndmask_b32_e64 v46, 0, 1, s[52:53]
	v_cmp_gt_f32_e64 s[52:53], v13, v43
	s_and_b64 s[56:57], s[56:57], s[46:47]
	v_addc_co_u32_e64 v6, s[48:49], v6, v45, s[48:49]
	s_or_b64 s[48:49], s[52:53], s[56:57]
	v_cmp_eq_f32_e64 s[52:53], v14, v43
	v_cmp_lt_u32_e64 s[56:57], 16, v42
	v_cmp_gt_f32_e64 s[50:51], v14, v43
	s_and_b64 s[28:29], s[52:53], s[56:57]
	s_or_b64 s[28:29], s[50:51], s[28:29]
	v_cmp_eq_f32_e64 s[52:53], v21, v43
	v_cmp_lt_u32_e64 s[56:57], 17, v42
	v_cndmask_b32_e64 v44, 0, 1, s[28:29]
	s_and_b64 s[28:29], s[52:53], s[56:57]
	v_cmp_eq_f32_e64 s[52:53], v19, v43
	v_cmp_lt_u32_e64 s[60:61], 18, v42
	v_cmp_gt_f32_e64 s[50:51], v21, v43
	s_and_b64 s[30:31], s[52:53], s[60:61]
	v_cmp_gt_f32_e64 s[52:53], v19, v43
	v_addc_co_u32_e64 v6, s[48:49], v6, v46, s[48:49]
	s_or_b64 s[30:31], s[52:53], s[30:31]
	v_cmp_eq_f32_e64 s[60:61], v15, v43
	v_cmp_lt_u32_e64 s[48:49], 19, v42
	s_or_b64 s[50:51], s[50:51], s[28:29]
	v_cndmask_b32_e64 v45, 0, 1, s[30:31]
	v_cmp_gt_f32_e64 s[52:53], v15, v43
	s_and_b64 s[30:31], s[60:61], s[48:49]
	v_addc_co_u32_e64 v6, s[50:51], v6, v44, s[50:51]
	v_cmp_eq_f32_e64 s[60:61], v16, v43
	v_cmp_lt_u32_e64 s[62:63], 20, v42
	s_or_b64 s[50:51], s[52:53], s[30:31]
	v_cmp_gt_f32_e64 s[52:53], v16, v43
	s_and_b64 s[28:29], s[60:61], s[62:63]
	s_or_b64 s[28:29], s[52:53], s[28:29]
	v_cmp_eq_f32_e64 s[62:63], v17, v43
	v_cmp_lt_u32_e64 s[60:61], 21, v42
	v_cndmask_b32_e64 v44, 0, 1, s[28:29]
	v_cmp_gt_f32_e64 s[52:53], v17, v43
	s_and_b64 s[28:29], s[62:63], s[60:61]
	v_addc_co_u32_e64 v6, s[50:51], v6, v45, s[50:51]
	s_or_b64 s[50:51], s[52:53], s[28:29]
	v_cmp_eq_f32_e64 s[52:53], v18, v43
	v_cmp_lt_u32_e64 s[62:63], 22, v42
	s_and_b64 s[28:29], s[52:53], s[62:63]
	v_cmp_gt_f32_e64 s[52:53], v18, v43
	s_or_b64 s[28:29], s[52:53], s[28:29]
	v_cmp_eq_f32_e64 s[64:65], v20, v43
	v_cmp_lt_u32_e64 s[52:53], 23, v42
	v_cndmask_b32_e64 v45, 0, 1, s[28:29]
	v_cmp_gt_f32_e64 s[62:63], v20, v43
	v_addc_co_u32_e64 v6, s[50:51], v6, v44, s[50:51]
	s_and_b64 s[28:29], s[64:65], s[52:53]
	s_or_b64 s[50:51], s[62:63], s[28:29]
	v_cmp_eq_f32_e64 s[62:63], v23, v43
	v_cmp_lt_u32_e64 s[64:65], 24, v42
	s_and_b64 s[28:29], s[62:63], s[64:65]
	v_cmp_gt_f32_e64 s[62:63], v23, v43
	s_or_b64 s[28:29], s[62:63], s[28:29]
	v_cmp_eq_f32_e64 s[62:63], v26, v43
	v_cmp_lt_u32_e64 s[64:65], 26, v42
	v_cndmask_b32_e64 v44, 0, 1, s[28:29]
	s_and_b64 s[28:29], s[62:63], s[64:65]
	v_cmp_gt_f32_e64 s[62:63], v26, v43
	s_or_b64 s[28:29], s[62:63], s[28:29]
	v_cmp_eq_f32_e64 s[62:63], v25, v43
	v_addc_co_u32_e64 v6, s[50:51], v6, v45, s[50:51]
	v_cmp_lt_u32_e64 s[64:65], 25, v42
	v_cndmask_b32_e64 v46, 0, 1, s[28:29]
	s_and_b64 s[28:29], s[62:63], s[64:65]
	v_cmp_gt_f32_e64 s[50:51], v25, v43
	s_or_b64 s[50:51], s[50:51], s[28:29]
	v_cmp_eq_f32_e64 s[62:63], v27, v43
	v_addc_co_u32_e64 v6, s[50:51], v6, v44, s[50:51]
	v_cmp_eq_u32_e64 s[50:51], 28, v42
	s_and_b64 s[28:29], s[50:51], s[62:63]
	v_cmp_gt_f32_e64 s[62:63], v27, v43
	v_or_b32_e32 v43, 1, v42
	v_cmp_eq_u32_e64 s[66:67], v43, v40
	v_cmp_eq_u32_e64 s[68:69], v43, v41
	s_or_b64 s[66:67], s[66:67], s[68:69]
	v_cndmask_b32_e64 v44, 0, v132, s[66:67]
	v_lshlrev_b32_e32 v43, 6, v43
	v_add_f32_e32 v3, v44, v3
	v_cmp_le_i32_e64 s[66:67], v43, v38
	s_or_b64 s[62:63], s[62:63], s[28:29]
	s_nop 0
	v_cndmask_b32_e64 v3, v162, v3, s[66:67]
	v_cmp_eq_f32_e64 s[66:67], v30, v3
	s_and_b64 s[28:29], vcc, s[66:67]
	v_cmp_gt_f32_e64 s[66:67], v30, v3
	s_or_b64 s[28:29], s[66:67], s[28:29]
	v_cmp_eq_f32_e64 s[66:67], v32, v3
	v_cndmask_b32_e64 v43, 0, 1, s[28:29]
	s_and_b64 s[28:29], vcc, s[66:67]
	v_cmp_gt_f32_e64 s[66:67], v32, v3
	s_or_b64 s[28:29], s[66:67], s[28:29]
	v_cmp_eq_f32_e64 s[66:67], v35, v3
	v_cndmask_b32_e64 v44, 0, 1, s[28:29]
	s_and_b64 s[28:29], s[66:67], s[42:43]
	v_cmp_gt_f32_e64 s[66:67], v35, v3
	s_or_b64 s[28:29], s[66:67], s[28:29]
	v_cmp_eq_f32_e64 s[66:67], v36, v3
	v_cndmask_b32_e64 v45, 0, 1, s[28:29]
	s_and_b64 s[28:29], s[66:67], s[40:41]
	v_cmp_gt_f32_e64 s[66:67], v36, v3
	s_or_b64 s[28:29], s[66:67], s[28:29]
	v_cmp_eq_f32_e64 s[66:67], v0, v3
	v_cndmask_b32_e64 v47, 0, 1, s[28:29]
	s_and_b64 s[28:29], s[66:67], s[54:55]
	v_cmp_gt_f32_e64 s[66:67], v0, v3
	s_or_b64 s[28:29], s[66:67], s[28:29]
	v_cmp_eq_f32_e64 s[66:67], v9, v3
	v_cndmask_b32_e64 v48, 0, 1, s[28:29]
	s_and_b64 s[28:29], s[66:67], s[44:45]
	v_cmp_gt_f32_e64 s[66:67], v9, v3
	s_or_b64 s[28:29], s[66:67], s[28:29]
	v_cmp_eq_f32_e64 s[66:67], v11, v3
	v_cndmask_b32_e64 v49, 0, 1, s[28:29]
	s_and_b64 s[28:29], s[66:67], s[58:59]
	v_cmp_gt_f32_e64 s[66:67], v11, v3
	s_or_b64 s[28:29], s[66:67], s[28:29]
	v_cmp_eq_f32_e64 s[66:67], v13, v3
	v_cndmask_b32_e64 v50, 0, 1, s[28:29]
	s_and_b64 s[28:29], s[66:67], s[46:47]
	v_cmp_gt_f32_e64 s[66:67], v13, v3
	s_or_b64 s[28:29], s[66:67], s[28:29]
	v_cmp_eq_f32_e64 s[66:67], v21, v3
	v_cndmask_b32_e64 v51, 0, 1, s[28:29]
	s_and_b64 s[28:29], s[66:67], s[56:57]
	v_cmp_gt_f32_e64 s[66:67], v21, v3
	s_or_b64 s[28:29], s[66:67], s[28:29]
	v_cmp_eq_f32_e64 s[66:67], v15, v3
	v_cndmask_b32_e64 v52, 0, 1, s[28:29]
	s_and_b64 s[28:29], s[66:67], s[48:49]
	v_cmp_gt_f32_e64 s[66:67], v15, v3
	s_or_b64 s[28:29], s[66:67], s[28:29]
	v_cmp_eq_f32_e64 s[66:67], v17, v3
	v_cndmask_b32_e64 v53, 0, 1, s[28:29]
	s_and_b64 s[28:29], s[66:67], s[60:61]
	v_cmp_gt_f32_e64 s[66:67], v17, v3
	s_or_b64 s[28:29], s[66:67], s[28:29]
	v_cmp_eq_f32_e64 s[66:67], v20, v3
	v_cndmask_b32_e64 v54, 0, 1, s[28:29]
	s_and_b64 s[28:29], s[66:67], s[52:53]
	v_cmp_gt_f32_e64 s[66:67], v20, v3
	s_or_b64 s[28:29], s[66:67], s[28:29]
	v_cmp_eq_f32_e64 s[66:67], v25, v3
	v_cndmask_b32_e64 v55, 0, 1, s[28:29]
	s_and_b64 s[28:29], s[66:67], s[64:65]
	v_cmp_gt_f32_e64 s[66:67], v25, v3
	s_or_b64 s[28:29], s[66:67], s[28:29]
	v_cmp_eq_f32_e64 s[66:67], v27, v3
	v_cndmask_b32_e64 v56, 0, 1, s[28:29]
	s_and_b64 s[28:29], s[50:51], s[66:67]
	v_cmp_gt_f32_e64 s[66:67], v27, v3
	s_or_b64 s[28:29], s[66:67], s[28:29]
	v_cmp_gt_f32_e64 s[66:67], v28, v3
	v_cndmask_b32_e64 v57, 0, 1, s[28:29]
	s_nop 0
	v_cndmask_b32_e64 v58, 0, 1, s[66:67]
	v_cmp_ge_f32_e64 s[66:67], v5, v3
	s_nop 1
	v_cndmask_b32_e64 v59, 0, 1, s[66:67]
	v_cmp_gt_f32_e64 s[66:67], v29, v3
	s_nop 1
	v_addc_co_u32_e64 v59, s[66:67], 0, v59, s[66:67]
	v_cmp_gt_f32_e64 s[66:67], v39, v3
	s_nop 1
	v_addc_co_u32_e64 v58, s[66:67], v59, v58, s[66:67]
	v_cmp_eq_f32_e64 s[66:67], v31, v3
	s_and_b64 s[28:29], vcc, s[66:67]
	v_cmp_gt_f32_e64 s[66:67], v31, v3
	s_or_b64 s[66:67], s[66:67], s[28:29]
	s_nop 0
	v_addc_co_u32_e64 v43, s[66:67], v58, v43, s[66:67]
	v_cmp_eq_f32_e64 s[66:67], v33, v3
	s_and_b64 s[28:29], vcc, s[66:67]
	v_cmp_gt_f32_e64 s[66:67], v33, v3
	s_or_b64 s[66:67], s[66:67], s[28:29]
	s_nop 0
	v_addc_co_u32_e64 v43, s[66:67], v43, v44, s[66:67]
	v_cmp_eq_f32_e64 s[66:67], v34, v3
	s_and_b64 s[28:29], s[66:67], s[42:43]
	v_cmp_gt_f32_e64 s[66:67], v34, v3
	s_or_b64 s[66:67], s[66:67], s[28:29]
	s_nop 0
	v_addc_co_u32_e64 v43, s[66:67], v43, v45, s[66:67]
	v_cmp_eq_f32_e64 s[66:67], v37, v3
	s_and_b64 s[28:29], s[66:67], s[40:41]
	v_cmp_gt_f32_e64 s[66:67], v37, v3
	s_or_b64 s[66:67], s[66:67], s[28:29]
	s_nop 0
	v_addc_co_u32_e64 v43, s[66:67], v43, v47, s[66:67]
	v_cmp_eq_f32_e64 s[66:67], v8, v3
	s_and_b64 s[28:29], s[66:67], s[54:55]
	v_cmp_gt_f32_e64 s[66:67], v8, v3
	s_or_b64 s[66:67], s[66:67], s[28:29]
	s_nop 0
	v_addc_co_u32_e64 v43, s[66:67], v43, v48, s[66:67]
	v_cmp_eq_f32_e64 s[66:67], v10, v3
	s_and_b64 s[28:29], s[66:67], s[44:45]
	v_cmp_gt_f32_e64 s[66:67], v10, v3
	s_or_b64 s[66:67], s[66:67], s[28:29]
	s_nop 0
	v_addc_co_u32_e64 v43, s[66:67], v43, v49, s[66:67]
	v_cmp_eq_f32_e64 s[66:67], v12, v3
	s_and_b64 s[28:29], s[66:67], s[58:59]
	v_cmp_gt_f32_e64 s[66:67], v12, v3
	s_or_b64 s[66:67], s[66:67], s[28:29]
	s_nop 0
	v_addc_co_u32_e64 v43, s[66:67], v43, v50, s[66:67]
	v_cmp_eq_f32_e64 s[66:67], v14, v3
	s_and_b64 s[28:29], s[66:67], s[46:47]
	v_cmp_gt_f32_e64 s[66:67], v14, v3
	s_or_b64 s[66:67], s[66:67], s[28:29]
	s_nop 0
	v_addc_co_u32_e64 v43, s[66:67], v43, v51, s[66:67]
	v_cmp_eq_f32_e64 s[66:67], v19, v3
	s_and_b64 s[28:29], s[66:67], s[56:57]
	v_cmp_gt_f32_e64 s[66:67], v19, v3
	s_or_b64 s[66:67], s[66:67], s[28:29]
	s_nop 0
	v_addc_co_u32_e64 v43, s[66:67], v43, v52, s[66:67]
	v_cmp_eq_f32_e64 s[66:67], v16, v3
	s_and_b64 s[28:29], s[66:67], s[48:49]
	v_cmp_gt_f32_e64 s[66:67], v16, v3
	s_or_b64 s[66:67], s[66:67], s[28:29]
	s_nop 0
	v_addc_co_u32_e64 v43, s[66:67], v43, v53, s[66:67]
	v_cmp_eq_f32_e64 s[66:67], v18, v3
	s_and_b64 s[28:29], s[66:67], s[60:61]
	v_cmp_gt_f32_e64 s[66:67], v18, v3
	s_or_b64 s[66:67], s[66:67], s[28:29]
	s_nop 0
	v_addc_co_u32_e64 v43, s[66:67], v43, v54, s[66:67]
	v_cmp_eq_f32_e64 s[66:67], v23, v3
	s_and_b64 s[28:29], s[66:67], s[52:53]
	v_cmp_gt_f32_e64 s[66:67], v23, v3
	s_or_b64 s[66:67], s[66:67], s[28:29]
	s_nop 0
	v_addc_co_u32_e64 v43, s[66:67], v43, v55, s[66:67]
	v_cmp_eq_f32_e64 s[66:67], v26, v3
	s_and_b64 s[28:29], s[66:67], s[64:65]
	v_cmp_gt_f32_e64 s[66:67], v26, v3
	s_or_b64 s[66:67], s[66:67], s[28:29]
	s_nop 0
	v_addc_co_u32_e64 v43, s[66:67], v43, v56, s[66:67]
	v_cmp_eq_f32_e64 s[66:67], v24, v3
	s_and_b64 s[28:29], s[50:51], s[66:67]
	v_cmp_gt_f32_e64 s[66:67], v24, v3
	v_or_b32_e32 v3, 2, v42
	v_cmp_eq_u32_e64 s[68:69], v3, v40
	v_cmp_eq_u32_e64 s[72:73], v3, v41
	s_or_b64 s[68:69], s[68:69], s[72:73]
	v_cndmask_b32_e64 v40, 0, v132, s[68:69]
	v_lshlrev_b32_e32 v41, 6, v3
	v_add_f32_e32 v4, v40, v4
	v_cmp_le_i32_e64 s[68:69], v41, v38
	s_or_b64 s[66:67], s[66:67], s[28:29]
	v_cmp_lt_u32_e64 s[72:73], 5, v3
	v_cndmask_b32_e64 v4, v162, v4, s[68:69]
	v_cmp_ge_f32_e64 s[68:69], v30, v4
	s_nop 1
	v_cndmask_b32_e64 v40, 0, 1, s[68:69]
	v_cmp_eq_f32_e64 s[68:69], v31, v4
	s_and_b64 s[28:29], vcc, s[68:69]
	v_cmp_gt_f32_e64 s[68:69], v31, v4
	s_or_b64 s[28:29], s[68:69], s[28:29]
	v_cmp_eq_f32_e64 s[68:69], v33, v4
	v_cndmask_b32_e64 v41, 0, 1, s[28:29]
	s_and_b64 s[28:29], vcc, s[68:69]
	v_cmp_gt_f32_e64 s[68:69], v33, v4
	s_or_b64 s[28:29], s[68:69], s[28:29]
	v_cmp_eq_f32_e64 s[68:69], v35, v4
	v_cndmask_b32_e64 v42, 0, 1, s[28:29]
	s_and_b64 s[28:29], s[68:69], s[72:73]
	v_cmp_eq_f32_e64 s[68:69], v34, v4
	s_and_b64 s[30:31], s[68:69], s[42:43]
	v_cmp_gt_f32_e64 s[42:43], v34, v4
	s_or_b64 s[30:31], s[42:43], s[30:31]
	v_cmp_eq_f32_e64 s[42:43], v37, v4
	v_cndmask_b32_e64 v44, 0, 1, s[30:31]
	s_and_b64 s[30:31], s[42:43], s[40:41]
	v_cmp_gt_f32_e64 s[42:43], v37, v4
	s_or_b64 s[30:31], s[42:43], s[30:31]
	v_cmp_eq_f32_e64 s[42:43], v0, v4
	v_cmp_lt_u32_e64 s[68:69], 9, v3
	v_cndmask_b32_e64 v45, 0, 1, s[30:31]
	s_and_b64 s[30:31], s[42:43], s[68:69]
	v_cmp_eq_f32_e64 s[42:43], v8, v4
	s_and_b64 s[54:55], s[42:43], s[54:55]
	v_cmp_gt_f32_e64 s[42:43], v8, v4
	s_or_b64 s[42:43], s[42:43], s[54:55]
	s_nop 0
	v_cndmask_b32_e64 v47, 0, 1, s[42:43]
	v_cmp_eq_f32_e64 s[42:43], v10, v4
	s_and_b64 s[54:55], s[42:43], s[44:45]
	v_cmp_gt_f32_e64 s[42:43], v10, v4
	s_or_b64 s[42:43], s[42:43], s[54:55]
	v_cmp_lt_u32_e64 s[54:55], 13, v3
	v_cndmask_b32_e64 v48, 0, 1, s[42:43]
	v_cmp_eq_f32_e64 s[42:43], v11, v4
	s_and_b64 s[68:69], s[42:43], s[54:55]
	v_cmp_eq_f32_e64 s[42:43], v12, v4
	s_and_b64 s[54:55], s[42:43], s[58:59]
	v_cmp_gt_f32_e64 s[42:43], v12, v4
	s_or_b64 s[42:43], s[42:43], s[54:55]
	s_nop 0
	v_cndmask_b32_e64 v49, 0, 1, s[42:43]
	v_cmp_eq_f32_e64 s[42:43], v14, v4
	s_and_b64 s[54:55], s[42:43], s[46:47]
	v_cmp_gt_f32_e64 s[42:43], v14, v4
	s_or_b64 s[42:43], s[42:43], s[54:55]
	v_cmp_lt_u32_e64 s[54:55], 17, v3
	v_cndmask_b32_e64 v50, 0, 1, s[42:43]
	v_cmp_eq_f32_e64 s[42:43], v21, v4
	s_and_b64 s[54:55], s[42:43], s[54:55]
	v_cmp_gt_f32_e64 s[42:43], v28, v4
	s_nop 1
	v_cndmask_b32_e64 v51, 0, 1, s[42:43]
	v_cmp_ge_f32_e64 s[42:43], v5, v4
	s_nop 1
	v_addc_co_u32_e64 v40, s[42:43], 0, v40, s[42:43]
	v_cmp_gt_f32_e64 s[42:43], v39, v4
	s_nop 1
	v_addc_co_u32_e64 v40, s[42:43], v40, v51, s[42:43]
	v_cmp_eq_f32_e64 s[42:43], v32, v4
	s_and_b64 s[58:59], vcc, s[42:43]
	v_cmp_gt_f32_e64 s[42:43], v32, v4
	s_or_b64 s[42:43], s[42:43], s[58:59]
	v_addc_co_u32_e64 v6, s[58:59], v6, v46, s[62:63]
	v_addc_co_u32_e64 v40, s[42:43], v40, v41, s[42:43]
	v_cmp_gt_f32_e64 s[42:43], v35, v4
	s_or_b64 s[42:43], s[42:43], s[28:29]
	v_cmp_gt_u32_e64 s[58:59], 16, v6
	v_addc_co_u32_e64 v40, s[42:43], v40, v42, s[42:43]
	v_cmp_eq_f32_e64 s[42:43], v36, v4
	s_and_b64 s[28:29], s[42:43], s[40:41]
	v_cmp_gt_f32_e64 s[42:43], v36, v4
	s_or_b64 s[42:43], s[42:43], s[28:29]
	s_nop 0
	v_addc_co_u32_e64 v40, s[42:43], v40, v44, s[42:43]
	v_cmp_gt_f32_e64 s[42:43], v0, v4
	s_or_b64 s[42:43], s[42:43], s[30:31]
	v_lshlrev_b32_e64 v44, v22, 1
	v_addc_co_u32_e64 v40, s[42:43], v40, v45, s[42:43]
	v_cmp_eq_f32_e64 s[42:43], v9, v4
	s_and_b64 s[28:29], s[42:43], s[44:45]
	v_cmp_gt_f32_e64 s[42:43], v9, v4
	s_or_b64 s[42:43], s[42:43], s[28:29]
	v_cndmask_b32_e64 v6, 0, v44, s[58:59]
	v_addc_co_u32_e64 v40, s[42:43], v40, v47, s[42:43]
	v_cmp_gt_f32_e64 s[42:43], v11, v4
	s_or_b64 s[42:43], s[42:43], s[68:69]
	v_cmp_eq_f32_e64 s[58:59], v27, v4
	v_addc_co_u32_e64 v40, s[42:43], v40, v48, s[42:43]
	v_cmp_eq_f32_e64 s[42:43], v13, v4
	s_and_b64 s[28:29], s[42:43], s[46:47]
	v_cmp_gt_f32_e64 s[42:43], v13, v4
	s_or_b64 s[42:43], s[42:43], s[28:29]
	v_lshlrev_b32_e32 v48, 6, v2
	v_addc_co_u32_e64 v40, s[42:43], v40, v49, s[42:43]
	v_cmp_gt_f32_e64 s[42:43], v21, v4
	s_or_b64 s[42:43], s[42:43], s[54:55]
	v_cmp_eq_f32_e64 s[54:55], v19, v4
	s_and_b64 s[28:29], s[54:55], s[56:57]
	v_cmp_gt_f32_e64 s[54:55], v19, v4
	v_addc_co_u32_e64 v40, s[42:43], v40, v50, s[42:43]
	s_or_b64 s[28:29], s[54:55], s[28:29]
	v_cmp_eq_f32_e64 s[42:43], v15, v4
	v_cndmask_b32_e64 v41, 0, 1, s[28:29]
	v_cmp_gt_f32_e64 s[54:55], v15, v4
	s_and_b64 s[28:29], s[42:43], s[48:49]
	s_or_b64 s[42:43], s[54:55], s[28:29]
	v_cmp_eq_f32_e64 s[54:55], v16, v4
	s_and_b64 s[28:29], s[54:55], s[48:49]
	v_cmp_gt_f32_e64 s[54:55], v16, v4
	s_or_b64 s[28:29], s[54:55], s[28:29]
	v_cmp_eq_f32_e64 s[54:55], v17, v4
	v_cmp_lt_u32_e64 s[56:57], 21, v3
	v_addc_co_u32_e64 v40, s[42:43], v40, v41, s[42:43]
	v_cndmask_b32_e64 v42, 0, 1, s[28:29]
	s_and_b64 s[28:29], s[54:55], s[56:57]
	v_cmp_gt_f32_e64 s[42:43], v17, v4
	v_cmp_eq_f32_e64 s[54:55], v18, v4
	s_or_b64 s[42:43], s[42:43], s[28:29]
	s_and_b64 s[28:29], s[54:55], s[60:61]
	v_cmp_gt_f32_e64 s[54:55], v18, v4
	s_or_b64 s[28:29], s[54:55], s[28:29]
	v_cmp_eq_f32_e64 s[56:57], v20, v4
	v_cndmask_b32_e64 v41, 0, 1, s[28:29]
	v_cmp_gt_f32_e64 s[54:55], v20, v4
	s_and_b64 s[28:29], s[56:57], s[52:53]
	v_addc_co_u32_e64 v40, s[42:43], v40, v42, s[42:43]
	v_cmp_eq_f32_e64 s[56:57], v23, v4
	s_or_b64 s[42:43], s[54:55], s[28:29]
	v_cmp_gt_f32_e64 s[54:55], v23, v4
	s_and_b64 s[28:29], s[56:57], s[52:53]
	s_or_b64 s[28:29], s[54:55], s[28:29]
	v_cmp_eq_f32_e64 s[54:55], v25, v4
	v_cmp_lt_u32_e64 s[56:57], 25, v3
	v_cndmask_b32_e64 v42, 0, 1, s[28:29]
	s_and_b64 s[28:29], s[54:55], s[56:57]
	v_cmp_eq_f32_e64 s[54:55], v26, v4
	s_and_b64 s[30:31], s[54:55], s[64:65]
	v_cmp_gt_f32_e64 s[54:55], v26, v4
	s_or_b64 s[30:31], s[54:55], s[30:31]
	v_cmp_eq_f32_e64 s[56:57], v24, v4
	v_cndmask_b32_e64 v3, 0, 1, s[30:31]
	v_cmp_gt_f32_e64 s[54:55], v24, v4
	s_and_b64 s[30:31], s[50:51], s[56:57]
	s_or_b64 s[30:31], s[54:55], s[30:31]
	v_cndmask_b32_e64 v47, 0, 1, s[30:31]
	v_cmp_ge_i32_e64 s[56:57], v38, v48
	s_and_b64 s[30:31], s[50:51], s[58:59]
	v_addc_co_u32_e64 v38, s[58:59], v43, v57, s[66:67]
	v_addc_co_u32_e64 v40, s[42:43], v40, v41, s[42:43]
	v_lshlrev_b32_e64 v45, v22, 2
	v_cmp_gt_f32_e64 s[54:55], v25, v4
	v_cmp_gt_u32_e64 s[58:59], 16, v38
	v_cmp_eq_f32_e64 s[42:43], v29, v4
	s_and_b64 s[60:61], s[50:51], s[42:43]
	v_cndmask_b32_e64 v38, 0, v45, s[58:59]
	s_or_b64 s[42:43], s[54:55], s[28:29]
	v_cndmask_b32_e64 v7, v162, v7, s[56:57]
	v_cmp_gt_f32_e64 s[56:57], v27, v4
	v_or_b32_e32 v6, v38, v6
	v_addc_co_u32_e64 v38, s[42:43], v40, v42, s[42:43]
	s_or_b64 s[42:43], s[56:57], s[30:31]
	v_cmp_gt_f32_e64 s[58:59], v29, v4
	v_addc_co_u32_e64 v3, s[42:43], v38, v3, s[42:43]
	s_or_b64 s[42:43], s[58:59], s[60:61]
	s_nop 0
	v_addc_co_u32_e64 v3, s[42:43], v3, v47, s[42:43]
	v_lshlrev_b32_e64 v4, v22, 4
	v_cmp_gt_u32_e64 s[42:43], 16, v3
	v_cmp_eq_f32_e64 s[54:55], v32, v7
	s_and_b64 s[28:29], vcc, s[54:55]
	v_cndmask_b32_e64 v3, 0, v4, s[42:43]
	v_cmp_ge_f32_e64 s[42:43], v30, v7
	v_cmp_lt_u32_e64 s[54:55], 4, v2
	v_cmp_lt_u32_e64 s[56:57], 5, v2
	v_cndmask_b32_e64 v4, 0, 1, s[42:43]
	v_cmp_ge_f32_e64 s[42:43], v5, v7
	v_cmp_gt_f32_e32 vcc, v33, v7
	s_nop 0
	v_addc_co_u32_e64 v4, s[42:43], 0, v4, s[42:43]
	v_cmp_ge_f32_e64 s[42:43], v31, v7
	s_nop 1
	v_cndmask_b32_e64 v5, 0, 1, s[42:43]
	v_cmp_gt_f32_e64 s[42:43], v32, v7
	s_or_b64 s[28:29], s[42:43], s[28:29]
	v_cmp_eq_f32_e64 s[42:43], v33, v7
	s_and_b64 s[58:59], s[42:43], s[54:55]
	v_cmp_eq_f32_e64 s[54:55], v35, v7
	v_cndmask_b32_e64 v30, 0, 1, s[28:29]
	v_cmp_gt_f32_e64 s[42:43], v35, v7
	s_and_b64 s[28:29], s[54:55], s[56:57]
	v_cmp_eq_f32_e64 s[54:55], v34, v7
	v_cmp_lt_u32_e64 s[56:57], 6, v2
	s_or_b64 s[28:29], s[42:43], s[28:29]
	s_and_b64 s[60:61], s[54:55], s[56:57]
	v_cmp_eq_f32_e64 s[56:57], v36, v7
	v_cndmask_b32_e64 v31, 0, 1, s[28:29]
	v_cmp_gt_f32_e64 s[54:55], v36, v7
	s_and_b64 s[28:29], s[56:57], s[40:41]
	s_or_b64 s[28:29], s[54:55], s[28:29]
	v_cmp_eq_f32_e64 s[54:55], v37, v7
	v_cmp_lt_u32_e64 s[56:57], 8, v2
	s_and_b64 s[56:57], s[54:55], s[56:57]
	v_cmp_gt_f32_e64 s[54:55], v39, v7
	s_or_b64 vcc, vcc, s[58:59]
	v_cmp_gt_f32_e64 s[42:43], v34, v7
	v_addc_co_u32_e64 v4, s[54:55], v4, v5, s[54:55]
	v_addc_co_u32_e32 v4, vcc, v4, v30, vcc
	s_or_b64 vcc, s[42:43], s[60:61]
	v_cmp_gt_f32_e64 s[40:41], v37, v7
	v_addc_co_u32_e32 v4, vcc, v4, v31, vcc
	v_cmp_eq_f32_e64 s[42:43], v0, v7
	v_cmp_lt_u32_e64 s[54:55], 9, v2
	v_cndmask_b32_e64 v32, 0, 1, s[28:29]
	s_or_b64 vcc, s[40:41], s[56:57]
	v_cmp_gt_f32_e64 s[40:41], v0, v7
	s_and_b64 s[28:29], s[42:43], s[54:55]
	s_or_b64 s[28:29], s[40:41], s[28:29]
	v_cmp_eq_f32_e64 s[42:43], v8, v7
	v_cmp_lt_u32_e64 s[54:55], 10, v2
	v_cndmask_b32_e64 v0, 0, 1, s[28:29]
	s_and_b64 s[28:29], s[42:43], s[54:55]
	v_cmp_eq_f32_e64 s[54:55], v9, v7
	v_cmp_gt_f32_e64 s[42:43], v9, v7
	s_and_b64 s[30:31], s[54:55], s[44:45]
	s_or_b64 s[30:31], s[42:43], s[30:31]
	v_cmp_eq_f32_e64 s[44:45], v10, v7
	v_cmp_lt_u32_e64 s[54:55], 12, v2
	v_cndmask_b32_e64 v5, 0, 1, s[30:31]
	s_and_b64 s[30:31], s[44:45], s[54:55]
	v_cmp_eq_f32_e64 s[54:55], v11, v7
	v_cmp_lt_u32_e64 s[56:57], 13, v2
	v_cmp_gt_f32_e64 s[44:45], v11, v7
	s_and_b64 s[54:55], s[54:55], s[56:57]
	s_or_b64 s[44:45], s[44:45], s[54:55]
	v_cmp_eq_f32_e64 s[54:55], v12, v7
	v_cmp_lt_u32_e64 s[56:57], 14, v2
	s_and_b64 s[58:59], s[54:55], s[56:57]
	v_cmp_eq_f32_e64 s[56:57], v13, v7
	v_cmp_gt_f32_e64 s[54:55], v13, v7
	s_and_b64 s[46:47], s[56:57], s[46:47]
	v_cmp_gt_f32_e64 s[40:41], v8, v7
	s_or_b64 s[46:47], s[54:55], s[46:47]
	v_cndmask_b32_e64 v9, 0, 1, s[46:47]
	v_cmp_eq_f32_e64 s[46:47], v14, v7
	v_cmp_lt_u32_e64 s[54:55], 16, v2
	v_addc_co_u32_e32 v4, vcc, v4, v32, vcc
	s_or_b64 s[40:41], s[40:41], s[28:29]
	v_cmp_gt_f32_e64 s[42:43], v10, v7
	s_and_b64 s[56:57], s[46:47], s[54:55]
	v_cmp_eq_f32_e64 s[46:47], v21, v7
	v_cmp_lt_u32_e64 s[54:55], 17, v2
	v_addc_co_u32_e64 v0, s[40:41], v4, v0, s[40:41]
	s_and_b64 s[54:55], s[46:47], s[54:55]
	v_cmp_gt_f32_e64 s[46:47], v21, v7
	s_or_b64 s[40:41], s[42:43], s[30:31]
	v_cndmask_b32_e64 v8, 0, 1, s[44:45]
	v_cmp_gt_f32_e64 s[44:45], v12, v7
	s_or_b64 s[46:47], s[46:47], s[54:55]
	v_addc_co_u32_e64 v0, s[40:41], v0, v5, s[40:41]
	v_cndmask_b32_e64 v10, 0, 1, s[46:47]
	v_cmp_eq_f32_e64 s[46:47], v19, v7
	v_cmp_lt_u32_e64 s[54:55], 18, v2
	s_or_b64 s[40:41], s[44:45], s[58:59]
	s_and_b64 s[54:55], s[46:47], s[54:55]
	v_cmp_gt_f32_e64 s[46:47], v14, v7
	v_addc_co_u32_e64 v0, s[40:41], v0, v8, s[40:41]
	s_or_b64 s[40:41], s[46:47], s[56:57]
	s_nop 0
	v_addc_co_u32_e64 v0, s[40:41], v0, v9, s[40:41]
	v_cmp_eq_f32_e64 s[42:43], v15, v7
	v_cmp_gt_f32_e64 s[40:41], v15, v7
	s_and_b64 s[28:29], s[42:43], s[48:49]
	s_or_b64 s[28:29], s[40:41], s[28:29]
	v_cmp_eq_f32_e64 s[42:43], v16, v7
	v_cmp_lt_u32_e64 s[44:45], 20, v2
	v_cndmask_b32_e64 v4, 0, 1, s[28:29]
	s_and_b64 s[28:29], s[42:43], s[44:45]
	v_cmp_eq_f32_e64 s[44:45], v17, v7
	v_cmp_lt_u32_e64 s[46:47], 21, v2
	v_cmp_gt_f32_e64 s[42:43], v17, v7
	s_and_b64 s[30:31], s[44:45], s[46:47]
	s_or_b64 s[30:31], s[42:43], s[30:31]
	v_cmp_eq_f32_e64 s[44:45], v18, v7
	v_cmp_lt_u32_e64 s[46:47], 22, v2
	v_cndmask_b32_e64 v5, 0, 1, s[30:31]
	s_and_b64 s[30:31], s[44:45], s[46:47]
	v_cmp_eq_f32_e64 s[46:47], v20, v7
	v_cmp_gt_f32_e64 s[44:45], v20, v7
	s_and_b64 s[46:47], s[46:47], s[52:53]
	v_cmp_gt_f32_e32 vcc, v19, v7
	s_or_b64 s[44:45], s[44:45], s[46:47]
	v_cmp_eq_f32_e64 s[46:47], v23, v7
	v_cmp_lt_u32_e64 s[48:49], 24, v2
	s_or_b64 vcc, vcc, s[54:55]
	s_and_b64 s[54:55], s[46:47], s[48:49]
	v_cmp_eq_f32_e64 s[48:49], v25, v7
	v_cmp_lt_u32_e64 s[52:53], 25, v2
	v_cmp_gt_f32_e64 s[40:41], v16, v7
	v_cmp_gt_f32_e64 s[46:47], v25, v7
	s_and_b64 s[48:49], s[48:49], s[52:53]
	v_addc_co_u32_e32 v0, vcc, v0, v10, vcc
	s_or_b64 s[46:47], s[46:47], s[48:49]
	v_cmp_eq_f32_e64 s[48:49], v26, v7
	v_cmp_lt_u32_e64 s[52:53], 26, v2
	s_or_b64 vcc, s[40:41], s[28:29]
	v_cmp_gt_f32_e64 s[42:43], v18, v7
	s_and_b64 s[56:57], s[48:49], s[52:53]
	v_cmp_eq_f32_e64 s[52:53], v27, v7
	v_addc_co_u32_e32 v0, vcc, v0, v4, vcc
	v_cmp_gt_f32_e64 s[48:49], v27, v7
	s_and_b64 s[52:53], s[50:51], s[52:53]
	s_or_b64 vcc, s[42:43], s[30:31]
	v_cndmask_b32_e64 v8, 0, 1, s[44:45]
	v_cmp_gt_f32_e64 s[44:45], v23, v7
	s_or_b64 s[48:49], s[48:49], s[52:53]
	v_addc_co_u32_e32 v0, vcc, v0, v5, vcc
	v_cndmask_b32_e64 v11, 0, 1, s[48:49]
	v_cmp_eq_f32_e64 s[48:49], v24, v7
	v_cmp_lt_u32_e64 s[52:53], 28, v2
	s_or_b64 vcc, s[44:45], s[54:55]
	v_cndmask_b32_e64 v9, 0, 1, s[46:47]
	v_cmp_gt_f32_e64 s[46:47], v26, v7
	s_and_b64 s[58:59], s[48:49], s[52:53]
	v_cmp_eq_f32_e64 s[48:49], v29, v7
	v_cmp_lt_u32_e64 s[52:53], 29, v2
	v_addc_co_u32_e32 v0, vcc, v0, v8, vcc
	s_and_b64 s[52:53], s[48:49], s[52:53]
	v_cmp_gt_f32_e64 s[48:49], v29, v7
	s_or_b64 vcc, s[46:47], s[56:57]
	s_or_b64 s[52:53], s[48:49], s[52:53]
	v_cmp_gt_f32_e64 s[48:49], v24, v7
	v_addc_co_u32_e32 v0, vcc, v0, v9, vcc
	v_cndmask_b32_e64 v2, 0, 1, s[52:53]
	v_cmp_eq_f32_e64 s[52:53], v28, v7
	s_or_b64 vcc, s[48:49], s[58:59]
	s_and_b64 s[52:53], s[50:51], s[52:53]
	v_cmp_gt_f32_e64 s[50:51], v28, v7
	v_addc_co_u32_e32 v0, vcc, v0, v11, vcc
	s_or_b64 vcc, s[50:51], s[52:53]
	s_nop 0
	v_addc_co_u32_e32 v0, vcc, v0, v2, vcc
	v_lshlrev_b32_e64 v2, v22, 8
	v_cmp_gt_u32_e32 vcc, 16, v0
	s_lshr_b32 s29, s23, 6
	s_lshl_b32 s28, 2, s29
	v_cndmask_b32_e32 v0, 0, v2, vcc
	v_or3_b32 v0, v6, v3, v0
	v_lshl_add_u32 v3, v120, 2, s25
	ds_or_b32 v3, v0
	v_lshlrev_b32_e32 v0, 2, v126
	v_lshlrev_b32_e32 v3, 2, v121
	v_mov_b32_e32 v2, s25
	v_add3_u32 v0, s25, v0, v3
	s_waitcnt lgkmcnt(0)
	s_barrier
	ds_read_b32 v133, v0
	ds_read_b128 v[2:5], v2
	v_mov_b32_e32 v0, s1
	v_readlane_b32 s1, v209, 23
	s_add_i32 s28, s28, -1
	s_cmpk_lt_u32 s23, 0x7c0
	v_mov_b32_e32 v10, s1
	v_readlane_b32 s1, v209, 24
	ds_read_b128 v[6:9], v0
	ds_read_b128 v[10:13], v10
	v_mov_b32_e32 v0, s1
	v_readlane_b32 s1, v209, 25
	s_cselect_b32 s23, s28, -1
	s_sub_i32 s22, 0x5e1, s22
	v_mov_b32_e32 v18, s1
	v_readlane_b32 s1, v209, 26
	ds_read_b128 v[14:17], v0
	ds_read_b128 v[18:21], v18
	v_mov_b32_e32 v0, s1
	v_readlane_b32 s1, v209, 27
	s_max_i32 s22, s22, 0
	s_lshr_b32 s22, s22, 6
	v_mov_b32_e32 v26, s1
	v_readlane_b32 s1, v209, 28
	ds_read_b128 v[22:25], v0
	ds_read_b128 v[26:29], v26
	v_mov_b32_e32 v0, s1
	ds_read_b128 v[30:33], v0
	s_waitcnt lgkmcnt(7)
	v_or_b32_e32 v0, v3, v2
	v_or_b32_e32 v0, v0, v4
	v_or_b32_e32 v0, v0, v5
	s_waitcnt lgkmcnt(6)
	v_or_b32_e32 v0, v0, v6
	v_or_b32_e32 v0, v0, v7
	v_or_b32_e32 v0, v0, v8
	v_or_b32_e32 v0, v0, v9
	s_waitcnt lgkmcnt(5)
	v_or_b32_e32 v0, v0, v10
	v_or_b32_e32 v0, v0, v11
	v_or_b32_e32 v0, v0, v12
	v_or_b32_e32 v0, v0, v13
	s_waitcnt lgkmcnt(4)
	v_or_b32_e32 v0, v0, v14
	v_or_b32_e32 v0, v0, v15
	v_or_b32_e32 v0, v0, v16
	v_or_b32_e32 v0, v0, v17
	s_waitcnt lgkmcnt(3)
	v_or_b32_e32 v0, v0, v18
	v_or_b32_e32 v0, v0, v19
	v_or_b32_e32 v0, v0, v20
	v_or_b32_e32 v0, v0, v21
	s_waitcnt lgkmcnt(2)
	v_or_b32_e32 v0, v0, v22
	v_or_b32_e32 v0, v0, v23
	v_or_b32_e32 v0, v0, v24
	v_or_b32_e32 v0, v0, v25
	s_waitcnt lgkmcnt(1)
	v_or_b32_e32 v0, v0, v26
	v_or_b32_e32 v0, v0, v27
	v_or_b32_e32 v0, v0, v28
	v_or_b32_e32 v0, v0, v29
	s_waitcnt lgkmcnt(0)
	v_or_b32_e32 v0, v0, v30
	v_or_b32_e32 v0, v0, v31
	v_or_b32_e32 v0, v0, v32
	v_or_b32_e32 v0, v0, v33
	s_load_dwordx2 s[0:1], s[12:13], 0x170
	v_readfirstlane_b32 s25, v0
	s_and_b32 s28, s25, s23
	s_bcnt1_i32_b32 s23, s28
	s_sub_i32 s25, s29, s22
	s_add_i32 s25, s25, s23
	s_add_i32 s25, s25, 1
	s_load_dwordx4 s[40:43], s[12:13], 0x1a8
	s_waitcnt lgkmcnt(0)
	s_add_u32 s29, s0, s24
	s_addc_u32 s30, s1, 0
	s_lshl_b32 s24, s79, 8
	s_add_u32 s44, s29, s24
	s_addc_u32 s45, s30, 0
	s_lshl_b32 s24, s82, 12
	s_add_u32 s24, s40, s24
	s_ff1_i32_b32 s31, s28
	v_ashrrev_i32_e32 v4, 4, v118
	s_addc_u32 s89, s41, 0
	s_lshl_b32 s40, s31, 6
	v_xor_b32_e32 v0, v4, v118
	s_ashr_i32 s41, s40, 31
	s_mul_i32 s34, s31, 0x94000
	v_lshlrev_b32_e32 v0, 3, v0
	s_mul_hi_i32 s47, s40, 0x2500
	s_add_u32 s46, s44, s34
	v_and_b32_e32 v0, 0x78, v0
	s_addc_u32 s47, s45, s47
	v_lshlrev_b32_e32 v2, 1, v0
	v_mov_b32_e32 v3, v1
	v_lshl_add_u64 v[8:9], s[46:47], 0, v[2:3]
	v_lshl_add_u32 v12, v171, 1, 16
	v_mad_i64_i32 v[6:7], s[46:47], v4, s33, v[8:9]
	s_mov_b64 s[48:49], 0xc00
	v_readfirstlane_b32 s34, v12
	v_lshl_add_u64 v[6:7], v[6:7], 0, s[48:49]
	s_mov_b32 m0, s34
	v_add_u32_e32 v5, 16, v4
	v_add_u32_e32 v0, 0x1000, v12
	global_load_lds_dwordx4 v[6:7], off
	v_mad_i64_i32 v[6:7], s[46:47], v5, s33, v[8:9]
	v_readfirstlane_b32 s34, v0
	v_add_u32_e32 v0, 0x2000, v12
	v_lshl_add_u64 v[6:7], v[6:7], 0, s[48:49]
	s_mov_b32 m0, s34
	v_readfirstlane_b32 s34, v0
	v_add_u32_e32 v0, 0x3000, v12
	global_load_lds_dwordx4 v[6:7], off
	s_mov_b32 m0, s34
	v_readfirstlane_b32 s34, v0
	v_lshrrev_b32_e32 v0, 3, v120
	v_add_u32_e32 v6, 32, v4
	v_xor_b32_e32 v0, v118, v0
	s_lshl_b64 s[40:41], s[40:41], 1
	v_mad_i64_i32 v[10:11], s[46:47], v6, s33, v[8:9]
	v_add_u32_e32 v7, 48, v4
	v_xor_b32_e32 v0, v0, v120
	v_ashrrev_i32_e32 v121, 31, v120
	s_add_u32 s40, s24, s40
	v_lshl_add_u64 v[10:11], v[10:11], 0, s[48:49]
	v_mad_i64_i32 v[8:9], s[46:47], v7, s33, v[8:9]
	v_lshlrev_b32_e32 v0, 3, v0
	s_addc_u32 s41, s89, s41
	global_load_lds_dwordx4 v[10:11], off
	v_lshl_add_u64 v[8:9], v[8:9], 0, s[48:49]
	s_mov_b32 m0, s34
	v_add_u32_e32 v10, 0x4000, v12
	v_lshlrev_b64 v[126:127], 12, v[120:121]
	v_and_b32_e32 v0, 56, v0
	global_load_lds_dwordx4 v[8:9], off
	v_lshl_add_u64 v[8:9], s[40:41], 0, v[126:127]
	v_lshlrev_b32_e32 v0, 1, v0
	v_readfirstlane_b32 s34, v10
	v_lshl_add_u64 v[8:9], v[8:9], 0, v[0:1]
	s_mov_b32 m0, s34
	s_mov_b64 s[46:47], 0x40000
	global_load_lds_dwordx4 v[8:9], off
	v_add_u32_e32 v8, 32, v120
	v_lshrrev_b32_e32 v10, 3, v8
	v_xor_b32_e32 v10, v118, v10
	v_xor_b32_e32 v10, v10, v120
	v_lshlrev_b32_e32 v10, 3, v10
	v_ashrrev_i32_e32 v9, 31, v8
	v_and_b32_e32 v10, 56, v10
	v_lshlrev_b64 v[128:129], 12, v[8:9]
	v_lshlrev_b32_e32 v136, 1, v10
	v_add_u32_e32 v10, 0x5000, v12
	v_lshl_add_u64 v[8:9], s[40:41], 0, v[128:129]
	v_readfirstlane_b32 s34, v10
	v_lshl_add_u64 v[8:9], v[8:9], 0, v[136:137]
	s_mov_b32 m0, s34
	v_lshl_add_u64 v[138:139], v[126:127], 0, s[46:47]
	v_add_u32_e32 v10, 0x6000, v12
	global_load_lds_dwordx4 v[8:9], off
	v_lshl_add_u64 v[8:9], s[40:41], 0, v[138:139]
	v_readfirstlane_b32 s34, v10
	v_lshl_add_u64 v[8:9], v[8:9], 0, v[0:1]
	s_mov_b32 m0, s34
	s_mov_b64 s[0:1], 0xc00
	global_load_lds_dwordx4 v[8:9], off
	v_add_u32_e32 v8, 0x60, v120
	v_lshrrev_b32_e32 v10, 3, v8
	v_xor_b32_e32 v10, v118, v10
	v_xor_b32_e32 v10, v10, v120
	v_lshlrev_b32_e32 v10, 3, v10
	v_ashrrev_i32_e32 v9, 31, v8
	v_and_b32_e32 v10, 56, v10
	v_lshlrev_b64 v[140:141], 12, v[8:9]
	v_lshlrev_b32_e32 v142, 1, v10
	v_add_u32_e32 v10, 0x7000, v12
	v_lshl_add_u64 v[8:9], s[40:41], 0, v[140:141]
	v_readfirstlane_b32 s34, v10
	v_lshl_add_u64 v[8:9], v[8:9], 0, v[142:143]
	s_mov_b32 m0, s34
	s_mov_b64 s[40:41], 0x1400
	global_load_lds_dwordx4 v[8:9], off
	s_cmp_lt_i32 s25, 1
	v_lshl_add_u64 v[120:121], v[66:67], 0, s[40:41]
	s_cbranch_scc1 .LBB0_296
	s_lshl_b32 s34, s79, 7
	s_lshl_b32 s46, s82, 11
	v_mad_i64_i32 v[144:145], s[40:41], v4, s33, 0
	v_mad_i64_i32 v[146:147], s[40:41], v5, s33, 0
	v_mad_i64_i32 v[148:149], s[40:41], v6, s33, 0
	v_mad_i64_i32 v[150:151], s[40:41], v7, s33, 0
	s_lshl_b32 s34, s34, 1
	s_add_u32 s40, s29, s34
	s_addc_u32 s41, s30, 0
	s_lshl_b32 s29, s46, 1
	v_lshl_add_u64 v[4:5], s[40:41], 0, v[2:3]
	s_mov_b64 s[40:41], 0x1000
	s_add_u32 s79, s42, s29
	v_lshl_add_u64 v[152:153], v[4:5], 0, s[40:41]
	v_lshl_add_u64 v[154:155], s[44:45], 0, v[2:3]
	v_or_b32_e32 v2, 32, v173
	v_or_b32_e32 v3, 0x60, v173
	v_and_b32_e32 v4, 15, v118
	v_lshrrev_b32_e32 v5, 3, v173
	s_addc_u32 s94, s43, 0
	s_add_i32 s29, s28, -1
	v_bitop3_b32 v174, v5, v118, 7 bitop3:0x78
	v_bitop3_b32 v5, v135, v118, 15 bitop3:0x78
	v_bitop3_b32 v6, v135, v4, 2 bitop3:0x36
	v_bitop3_b32 v7, v135, v4, 4 bitop3:0x36
	v_bitop3_b32 v8, v135, v4, 6 bitop3:0x36
	v_bitop3_b32 v9, v135, v4, 8 bitop3:0x36
	v_bitop3_b32 v10, v135, v4, 10 bitop3:0x36
	v_bitop3_b32 v11, v135, v4, 12 bitop3:0x36
	v_bitop3_b32 v4, v135, v4, 14 bitop3:0x36
	v_lshrrev_b32_e32 v12, 3, v2
	v_lshlrev_b32_e32 v177, 7, v2
	v_lshrrev_b32_e32 v2, 3, v3
	v_mov_b32_e32 v16, v1
	v_mov_b32_e32 v17, v1
	s_and_b32 s28, s29, s28
	v_bitop3_b32 v176, v12, v118, 7 bitop3:0x78
	v_bitop3_b32 v178, v2, 7, v118 bitop3:0x48
	v_lshlrev_b32_e32 v179, 7, v3
	v_lshlrev_b32_e32 v180, 4, v5
	v_lshlrev_b32_e32 v181, 4, v6
	v_lshlrev_b32_e32 v182, 4, v7
	v_lshlrev_b32_e32 v183, 4, v8
	v_lshlrev_b32_e32 v184, 4, v9
	v_lshlrev_b32_e32 v185, 4, v10
	v_lshlrev_b32_e32 v186, 4, v11
	v_lshlrev_b32_e32 v187, 4, v4
	v_mov_b32_e32 v2, v1
	v_mov_b32_e32 v3, v1
	v_mov_b32_e32 v4, v1
	v_mov_b32_e32 v5, v1
	v_mov_b32_e32 v6, v1
	v_mov_b32_e32 v7, v1
	v_mov_b32_e32 v8, v1
	v_mov_b32_e32 v9, v1
	v_mov_b32_e32 v10, v1
	v_mov_b32_e32 v11, v1
	v_mov_b32_e32 v12, v1
	v_mov_b32_e32 v13, v1
	v_mov_b32_e32 v14, v1
	v_mov_b32_e32 v15, v1
	v_mov_b64_e32 v[32:33], v[16:17]
	v_mov_b64_e32 v[48:49], v[16:17]
	v_mov_b64_e32 v[64:65], v[16:17]
	v_lshlrev_b32_e32 v175, 7, v173
	v_lshlrev_b32_e32 v173, 8, v173
	v_sub_u32_e32 v188, v117, v115
	s_add_i32 s95, s23, -1
	s_mov_b32 s29, 0
	v_mov_b32_e32 v67, 0x41a00000
	v_mov_b32_e32 v66, 0
	v_mov_b32_e32 v189, s28
	v_mov_b64_e32 v[30:31], v[14:15]
	v_mov_b64_e32 v[28:29], v[12:13]
	v_mov_b64_e32 v[26:27], v[10:11]
	v_mov_b64_e32 v[24:25], v[8:9]
	v_mov_b64_e32 v[22:23], v[6:7]
	v_mov_b64_e32 v[20:21], v[4:5]
	v_mov_b64_e32 v[18:19], v[2:3]
	v_mov_b64_e32 v[46:47], v[14:15]
	v_mov_b64_e32 v[44:45], v[12:13]
	v_mov_b64_e32 v[42:43], v[10:11]
	v_mov_b64_e32 v[40:41], v[8:9]
	v_mov_b64_e32 v[38:39], v[6:7]
	v_mov_b64_e32 v[36:37], v[4:5]
	v_mov_b64_e32 v[34:35], v[2:3]
	v_mov_b64_e32 v[62:63], v[14:15]
	v_mov_b64_e32 v[60:61], v[12:13]
	v_mov_b64_e32 v[58:59], v[10:11]
	v_mov_b64_e32 v[56:57], v[8:9]
	v_mov_b64_e32 v[54:55], v[6:7]
	v_mov_b64_e32 v[52:53], v[4:5]
	v_mov_b64_e32 v[50:51], v[2:3]
	v_readfirstlane_b32 s32, v117
	s_and_b32 s32, s32, 0xffffffe0
	s_mov_b32 s28, s31

.LBB0_320:
	s_cmp_ge_u32 s29, s23
	s_cselect_b64 s[44:45], -1, 0
	s_lshl_b32 s34, 1, s31
	v_and_b32_e32 v68, s34, v133
	s_lshl_b32 s31, s31, 6
	v_cmp_ne_u32_e32 vcc, 0, v68
	v_cmp_le_i32_e64 s[40:41], s31, v117
	s_and_b64 s[40:41], s[40:41], vcc
	s_or_b64 s[40:41], s[44:45], s[40:41]
	s_mov_b64 vcc, s[40:41]
	s_cbranch_vccz .LBB0_323
	s_add_i32 s34, 16, 0x8000
	s_and_b64 s[46:47], s[42:43], exec
	s_cselect_b32 s46, 16, s34
	s_add_i32 s34, 16, 0xc000
	s_add_i32 s47, 16, 0x4000
	s_and_b64 s[42:43], s[42:43], exec
	s_cselect_b32 s47, s47, s34
	s_sub_i32 s82, 0, s31
	s_and_b64 s[42:43], s[44:45], exec
	s_brev_b32 s31, 1
	v_lshlrev_b32_e32 v68, 1, v115
	s_mov_b32 s34, 0
	s_cselect_b32 s31, 0x200, s31
	v_add3_u32 v137, s47, v175, v68
	v_add3_u32 v143, s47, v177, v68
	v_add3_u32 v190, s47, v179, v68
	v_add_u32_e32 v191, s46, v173
	s_mov_b64 s[86:87], -1
	s_sub_i32 s42, 0, s82
	s_add_i32 s43, s42, 63
	s_cmp_le_i32 s43, s32
	s_cbranch_scc0 .LBB0_322
	s_cmpk_lg_u32 s31, 0x200
	s_cbranch_scc1 .Lnsa_fast
	s_sub_i32 s43, s32, 0x1e0
	s_cmp_ge_i32 s42, s43
	s_cbranch_scc0 .LBB0_322
.Lnsa_fast:
	s_sub_i32 s42, 0, s82
	v_sub_u32_e32 v80, s42, v188
	v_lshl_add_u32 v192, v174, 4, v137
	v_lshl_add_u32 v193, v176, 4, v143
	v_lshl_add_u32 v208, v178, 4, v190
	v_cvt_f32_i32_e32 v80, v80
	v_mul_f32_e32 v78, 0x40faf232, v119
	v_add_u32_e32 v192, -16, v192
	v_add_u32_e32 v193, -16, v193
	v_add_u32_e32 v208, -16, v208
	v_fmaak_f32 v76, v78, v80, 0xc31cd760
	v_add_u32_e32 v81, v191, v180
	ds_read_b128 v[244:247], v81
	v_add_u32_e32 v118, v191, v181
	ds_read_b128 v[248:251], v118
	v_add_u32_e32 v135, v191, v182
	ds_read_b128 v[252:255], v135
	v_add_u32_e32 v211, v191, v183
	ds_read_b128 v[196:199], v211
	v_add_u32_e32 v79, v191, v184
	ds_read_b128 v[200:203], v79
	v_add_u32_e32 v80, v191, v185
	ds_read_b128 v[204:207], v80
	v_add_u32_e32 v81, v191, v186
	ds_read_b128 v[68:71], v81
	v_add_u32_e32 v118, v191, v187
	ds_read_b128 v[72:75], v118
	v_fmamk_f32 v77, v78, 0x42000000, v76
	v_cndmask_b32_e64 v76, v162, v76, s[40:41]
	v_cndmask_b32_e64 v77, v162, v77, s[40:41]
	v_mov_b32_e32 v212, v76
	v_fmamk_f32 v213, v78, 0x3f800000, v76
	v_fmamk_f32 v214, v78, 0x40000000, v76
	v_fmamk_f32 v215, v78, 0x40400000, v76
	v_fmamk_f32 v216, v78, 0x41000000, v76
	v_fmamk_f32 v217, v78, 0x41100000, v76
	v_fmamk_f32 v218, v78, 0x41200000, v76
	v_fmamk_f32 v219, v78, 0x41300000, v76
	v_fmamk_f32 v220, v78, 0x41800000, v76
	v_fmamk_f32 v221, v78, 0x41880000, v76
	v_fmamk_f32 v222, v78, 0x41900000, v76
	v_fmamk_f32 v223, v78, 0x41980000, v76
	v_fmamk_f32 v224, v78, 0x41c00000, v76
	v_fmamk_f32 v225, v78, 0x41c80000, v76
	v_fmamk_f32 v226, v78, 0x41d00000, v76
	v_fmamk_f32 v227, v78, 0x41d80000, v76
	s_waitcnt lgkmcnt(7)
	s_nop 0
	v_mfma_f32_32x32x16_bf16 v[212:227], v[244:247], v[82:85], v[212:227]
	v_add_u32_e32 v135, v191, v180
	ds_read_b128 v[244:247], v135 offset:8192
	v_mov_b32_e32 v228, v77
	v_fmamk_f32 v229, v78, 0x3f800000, v77
	s_waitcnt lgkmcnt(7)
	v_mfma_f32_32x32x16_bf16 v[212:227], v[248:251], v[86:89], v[212:227]
	v_add_u32_e32 v211, v191, v181
	ds_read_b128 v[248:251], v211 offset:8192
	v_fmamk_f32 v230, v78, 0x40000000, v77
	v_fmamk_f32 v231, v78, 0x40400000, v77
	s_waitcnt lgkmcnt(7)
	v_mfma_f32_32x32x16_bf16 v[212:227], v[252:255], v[90:93], v[212:227]
	v_add_u32_e32 v79, v191, v182
	ds_read_b128 v[252:255], v79 offset:8192
	v_fmamk_f32 v232, v78, 0x41000000, v77
	v_fmamk_f32 v233, v78, 0x41100000, v77
	s_waitcnt lgkmcnt(7)
	v_mfma_f32_32x32x16_bf16 v[212:227], v[196:199], v[94:97], v[212:227]
	v_add_u32_e32 v80, v191, v183
	ds_read_b128 v[196:199], v80 offset:8192
	v_fmamk_f32 v234, v78, 0x41200000, v77
	v_fmamk_f32 v235, v78, 0x41300000, v77
	s_waitcnt lgkmcnt(7)
	v_mfma_f32_32x32x16_bf16 v[212:227], v[200:203], v[98:101], v[212:227]
	v_add_u32_e32 v81, v191, v184
	ds_read_b128 v[200:203], v81 offset:8192
	v_fmamk_f32 v236, v78, 0x41800000, v77
	v_fmamk_f32 v237, v78, 0x41880000, v77
	s_waitcnt lgkmcnt(7)
	v_mfma_f32_32x32x16_bf16 v[212:227], v[204:207], v[102:105], v[212:227]
	v_add_u32_e32 v118, v191, v185
	ds_read_b128 v[204:207], v118 offset:8192
	v_fmamk_f32 v238, v78, 0x41900000, v77
	v_fmamk_f32 v239, v78, 0x41980000, v77
	s_waitcnt lgkmcnt(7)
	v_mfma_f32_32x32x16_bf16 v[212:227], v[68:71], v[106:109], v[212:227]
	v_add_u32_e32 v135, v191, v186
	ds_read_b128 v[68:71], v135 offset:8192
	v_fmamk_f32 v240, v78, 0x41c00000, v77
	v_fmamk_f32 v241, v78, 0x41c80000, v77
	s_waitcnt lgkmcnt(7)
	v_mfma_f32_32x32x16_bf16 v[212:227], v[72:75], v[110:113], v[212:227]
	v_add_u32_e32 v211, v191, v187
	ds_read_b128 v[72:75], v211 offset:8192
	v_fmamk_f32 v242, v78, 0x41d00000, v77
	v_fmamk_f32 v243, v78, 0x41d80000, v77
	s_waitcnt lgkmcnt(7)
	s_nop 0
	v_mfma_f32_32x32x16_bf16 v[228:243], v[244:247], v[82:85], v[228:243]
	ds_read_b64 v[244:245], v192 offset:16
	v_xor_b32_e32 v79, 16, v192
	ds_read_b64 v[246:247], v79 offset:16
	s_waitcnt lgkmcnt(8)
	v_mfma_f32_32x32x16_bf16 v[228:243], v[248:251], v[86:89], v[228:243]
	ds_read_b64 v[248:249], v193 offset:16
	v_xor_b32_e32 v80, 16, v193
	ds_read_b64 v[250:251], v80 offset:16
	s_waitcnt lgkmcnt(9)
	v_mfma_f32_32x32x16_bf16 v[228:243], v[252:255], v[90:93], v[228:243]
	ds_read_b64 v[252:253], v192 offset:8208
	v_xor_b32_e32 v81, 16, v192
	ds_read_b64 v[254:255], v81 offset:8208
	s_waitcnt lgkmcnt(10)
	v_mfma_f32_32x32x16_bf16 v[228:243], v[196:199], v[94:97], v[228:243]
	ds_read_b64 v[196:197], v208 offset:16
	v_xor_b32_e32 v118, 16, v208
	ds_read_b64 v[198:199], v118 offset:16
	v_mul_f32_e32 v212, s37, v212
	v_mul_f32_e32 v213, s37, v213
	v_mul_f32_e32 v214, s37, v214
	v_mul_f32_e32 v215, s37, v215
	v_mul_f32_e32 v216, s37, v216
	v_mul_f32_e32 v217, s37, v217
	s_waitcnt lgkmcnt(11)
	v_mfma_f32_32x32x16_bf16 v[228:243], v[200:203], v[98:101], v[228:243]
	v_xor_b32_e32 v135, 32, v192
	ds_read_b64 v[200:201], v135 offset:16
	v_xor_b32_e32 v211, 48, v192
	ds_read_b64 v[202:203], v211 offset:16
	v_mul_f32_e32 v218, s37, v218
	v_mul_f32_e32 v219, s37, v219
	v_exp_f32_e32 v212, v212
	v_exp_f32_e32 v213, v213
	v_exp_f32_e32 v214, v214
	v_exp_f32_e32 v215, v215
	s_waitcnt lgkmcnt(12)
	v_mfma_f32_32x32x16_bf16 v[228:243], v[204:207], v[102:105], v[228:243]
	v_xor_b32_e32 v79, 32, v193
	ds_read_b64 v[204:205], v79 offset:16
	v_xor_b32_e32 v80, 48, v193
	ds_read_b64 v[206:207], v80 offset:16
	v_exp_f32_e32 v216, v216
	v_exp_f32_e32 v217, v217
	v_exp_f32_e32 v218, v218
	v_exp_f32_e32 v219, v219
	v_add_f32_e32 v66, v66, v212
	v_add_f32_e32 v66, v66, v213
	s_waitcnt lgkmcnt(13)
	v_mfma_f32_32x32x16_bf16 v[228:243], v[68:71], v[106:109], v[228:243]
	v_xor_b32_e32 v81, 32, v192
	ds_read_b64 v[68:69], v81 offset:8208
	v_xor_b32_e32 v118, 48, v192
	ds_read_b64 v[70:71], v118 offset:8208
	v_cvt_pk_bf16_f32 v212, v212, v213
	v_add_f32_e32 v66, v66, v214
	v_add_f32_e32 v66, v66, v215
	v_cvt_pk_bf16_f32 v213, v214, v215
	v_add_f32_e32 v66, v66, v216
	v_add_f32_e32 v66, v66, v217
	s_waitcnt lgkmcnt(14)
	v_mfma_f32_32x32x16_bf16 v[228:243], v[72:75], v[110:113], v[228:243]
	v_xor_b32_e32 v135, 32, v208
	ds_read_b64 v[72:73], v135 offset:16
	v_xor_b32_e32 v211, 48, v208
	ds_read_b64 v[74:75], v211 offset:16
	v_cvt_pk_bf16_f32 v214, v216, v217
	v_add_f32_e32 v66, v66, v218
	v_add_f32_e32 v66, v66, v219
	v_cvt_pk_bf16_f32 v215, v218, v219
	s_waitcnt lgkmcnt(14)
	s_nop 0
	v_mfma_f32_32x32x16_bf16 v[50:65], v[244:247], v[212:215], v[50:65]
	v_xor_b32_e32 v79, 64, v192
	ds_read_b64 v[244:245], v79 offset:16
	v_xor_b32_e32 v80, 0x50, v192
	ds_read_b64 v[246:247], v80 offset:16
	v_mul_f32_e32 v220, s37, v220
	v_mul_f32_e32 v221, s37, v221
	v_mul_f32_e32 v222, s37, v222
	v_mul_f32_e32 v223, s37, v223
	v_mul_f32_e32 v224, s37, v224
	v_mul_f32_e32 v225, s37, v225
	v_mul_f32_e32 v226, s37, v226
	s_waitcnt lgkmcnt(14)
	v_mfma_f32_32x32x16_bf16 v[34:49], v[248:251], v[212:215], v[34:49]
	v_xor_b32_e32 v81, 64, v193
	ds_read_b64 v[248:249], v81 offset:16
	v_xor_b32_e32 v118, 0x50, v193
	ds_read_b64 v[250:251], v118 offset:16
	v_mul_f32_e32 v227, s37, v227
	v_exp_f32_e32 v220, v220
	v_exp_f32_e32 v221, v221
	v_exp_f32_e32 v222, v222
	v_exp_f32_e32 v223, v223
	v_exp_f32_e32 v224, v224
	v_exp_f32_e32 v225, v225
	s_waitcnt lgkmcnt(14)
	v_mfma_f32_32x32x16_bf16 v[18:33], v[252:255], v[212:215], v[18:33]
	v_xor_b32_e32 v135, 64, v192
	ds_read_b64 v[252:253], v135 offset:8208
	v_xor_b32_e32 v211, 0x50, v192
	ds_read_b64 v[254:255], v211 offset:8208
	v_exp_f32_e32 v226, v226
	v_exp_f32_e32 v227, v227
	v_add_f32_e32 v66, v66, v220
	v_add_f32_e32 v66, v66, v221
	v_cvt_pk_bf16_f32 v220, v220, v221
	v_add_f32_e32 v66, v66, v222
	v_add_f32_e32 v66, v66, v223
	s_waitcnt lgkmcnt(14)
	v_mfma_f32_32x32x16_bf16 v[2:17], v[196:199], v[212:215], v[2:17]
	v_xor_b32_e32 v79, 64, v208
	ds_read_b64 v[196:197], v79 offset:16
	v_xor_b32_e32 v80, 0x50, v208
	ds_read_b64 v[198:199], v80 offset:16
	v_cvt_pk_bf16_f32 v221, v222, v223
	v_add_f32_e32 v66, v66, v224
	v_add_f32_e32 v66, v66, v225
	v_cvt_pk_bf16_f32 v222, v224, v225
	v_add_f32_e32 v66, v66, v226
	v_add_f32_e32 v66, v66, v227
	v_cvt_pk_bf16_f32 v223, v226, v227
	s_waitcnt lgkmcnt(14)
	s_nop 0
	v_mfma_f32_32x32x16_bf16 v[50:65], v[200:203], v[220:223], v[50:65]
	v_xor_b32_e32 v81, 0x60, v192
	ds_read_b64 v[200:201], v81 offset:16
	v_xor_b32_e32 v118, 0x70, v192
	ds_read_b64 v[202:203], v118 offset:16
	v_mul_f32_e32 v228, s37, v228
	v_mul_f32_e32 v229, s37, v229
	v_mul_f32_e32 v230, s37, v230
	v_mul_f32_e32 v231, s37, v231
	v_mul_f32_e32 v232, s37, v232
	v_mul_f32_e32 v233, s37, v233
	v_mul_f32_e32 v234, s37, v234
	s_waitcnt lgkmcnt(14)
	v_mfma_f32_32x32x16_bf16 v[34:49], v[204:207], v[220:223], v[34:49]
	v_xor_b32_e32 v135, 0x60, v193
	ds_read_b64 v[204:205], v135 offset:16
	v_xor_b32_e32 v211, 0x70, v193
	ds_read_b64 v[206:207], v211 offset:16
	v_mul_f32_e32 v235, s37, v235
	v_exp_f32_e32 v228, v228
	v_exp_f32_e32 v229, v229
	v_exp_f32_e32 v230, v230
	v_exp_f32_e32 v231, v231
	v_exp_f32_e32 v232, v232
	v_exp_f32_e32 v233, v233
	s_waitcnt lgkmcnt(14)
	v_mfma_f32_32x32x16_bf16 v[18:33], v[68:71], v[220:223], v[18:33]
	v_xor_b32_e32 v79, 0x60, v192
	ds_read_b64 v[68:69], v79 offset:8208
	v_xor_b32_e32 v80, 0x70, v192
	ds_read_b64 v[70:71], v80 offset:8208
	v_exp_f32_e32 v234, v234
	v_exp_f32_e32 v235, v235
	v_add_f32_e32 v66, v66, v228
	v_add_f32_e32 v66, v66, v229
	v_cvt_pk_bf16_f32 v228, v228, v229
	v_add_f32_e32 v66, v66, v230
	v_add_f32_e32 v66, v66, v231
	s_waitcnt lgkmcnt(14)
	v_mfma_f32_32x32x16_bf16 v[2:17], v[72:75], v[220:223], v[2:17]
	v_xor_b32_e32 v81, 0x60, v208
	ds_read_b64 v[72:73], v81 offset:16
	v_xor_b32_e32 v118, 0x70, v208
	ds_read_b64 v[74:75], v118 offset:16
	v_cvt_pk_bf16_f32 v229, v230, v231
	v_add_f32_e32 v66, v66, v232
	v_add_f32_e32 v66, v66, v233
	v_cvt_pk_bf16_f32 v230, v232, v233
	v_add_f32_e32 v66, v66, v234
	v_add_f32_e32 v66, v66, v235
	v_cvt_pk_bf16_f32 v231, v234, v235
	s_waitcnt lgkmcnt(14)
	s_nop 0
	v_mfma_f32_32x32x16_bf16 v[50:65], v[244:247], v[228:231], v[50:65]
	v_mul_f32_e32 v236, s37, v236
	v_mul_f32_e32 v237, s37, v237
	v_mul_f32_e32 v238, s37, v238
	v_mul_f32_e32 v239, s37, v239
	v_mul_f32_e32 v240, s37, v240
	v_mul_f32_e32 v241, s37, v241
	v_mul_f32_e32 v242, s37, v242
	s_waitcnt lgkmcnt(12)
	v_mfma_f32_32x32x16_bf16 v[34:49], v[248:251], v[228:231], v[34:49]
	v_mul_f32_e32 v243, s37, v243
	v_exp_f32_e32 v236, v236
	v_exp_f32_e32 v237, v237
	v_exp_f32_e32 v238, v238
	v_exp_f32_e32 v239, v239
	v_exp_f32_e32 v240, v240
	v_exp_f32_e32 v241, v241
	s_waitcnt lgkmcnt(10)
	v_mfma_f32_32x32x16_bf16 v[18:33], v[252:255], v[228:231], v[18:33]
	v_exp_f32_e32 v242, v242
	v_exp_f32_e32 v243, v243
	v_add_f32_e32 v66, v66, v236
	v_add_f32_e32 v66, v66, v237
	v_cvt_pk_bf16_f32 v236, v236, v237
	v_add_f32_e32 v66, v66, v238
	v_add_f32_e32 v66, v66, v239
	s_waitcnt lgkmcnt(8)
	v_mfma_f32_32x32x16_bf16 v[2:17], v[196:199], v[228:231], v[2:17]
	v_cvt_pk_bf16_f32 v237, v238, v239
	v_add_f32_e32 v66, v66, v240
	v_add_f32_e32 v66, v66, v241
	v_cvt_pk_bf16_f32 v238, v240, v241
	v_add_f32_e32 v66, v66, v242
	v_add_f32_e32 v66, v66, v243
	v_cvt_pk_bf16_f32 v239, v242, v243
	s_waitcnt lgkmcnt(6)
	s_nop 0
	v_mfma_f32_32x32x16_bf16 v[50:65], v[200:203], v[236:239], v[50:65]
	s_waitcnt lgkmcnt(4)
	v_mfma_f32_32x32x16_bf16 v[34:49], v[204:207], v[236:239], v[34:49]
	s_waitcnt lgkmcnt(2)
	v_mfma_f32_32x32x16_bf16 v[18:33], v[68:71], v[236:239], v[18:33]
	s_waitcnt lgkmcnt(0)
	v_mfma_f32_32x32x16_bf16 v[2:17], v[72:75], v[236:239], v[2:17]
	s_branch .LBB0_323

.LBB0_323:
	s_cmp_lg_u32 s29, s95
	s_cbranch_scc1 .LBB0_325
	ds_bpermute_b32 v67, v172, v66
	global_load_dword v68, v[124:125], off offset:4
	s_waitcnt lgkmcnt(0)
	v_add_f32_e32 v66, v66, v67
	global_load_ushort v67, v[120:121], off offset:2
	v_cmp_lt_f32_e32 vcc, 0, v66
	v_rcp_f32_e32 v66, v66
	s_waitcnt vmcnt(0)
	v_lshlrev_b32_e32 v67, 16, v67
	v_add_f32_e32 v67, v68, v67
	global_load_dwordx4 v[68:71], v[122:123], off
	v_mul_f32_e32 v67, 0xbfb8aa3b, v67
	v_exp_f32_e32 v67, v67
	v_cndmask_b32_e32 v66, 0, v66, vcc
	v_add_f32_e32 v67, 1.0, v67
	v_rcp_f32_e32 v67, v67
	s_nop 0
	v_mul_f32_e32 v66, v66, v67
	s_waitcnt vmcnt(0)
	v_pk_fma_f32 v[50:51], v[50:51], v[66:67], v[68:69] op_sel_hi:[1,0,1]
	v_pk_fma_f32 v[52:53], v[52:53], v[66:67], v[70:71] op_sel_hi:[1,0,1]
	global_store_dwordx4 v[122:123], v[50:53], off
	global_load_dwordx4 v[50:53], v[122:123], off offset:32
	s_waitcnt vmcnt(0)
	v_pk_fma_f32 v[50:51], v[54:55], v[66:67], v[50:51] op_sel_hi:[1,0,1]
	v_pk_fma_f32 v[52:53], v[56:57], v[66:67], v[52:53] op_sel_hi:[1,0,1]
	global_store_dwordx4 v[122:123], v[50:53], off offset:32
	global_load_dwordx4 v[50:53], v[122:123], off offset:64
	s_waitcnt vmcnt(0)
	v_pk_fma_f32 v[50:51], v[58:59], v[66:67], v[50:51] op_sel_hi:[1,0,1]
	v_pk_fma_f32 v[52:53], v[60:61], v[66:67], v[52:53] op_sel_hi:[1,0,1]
	global_store_dwordx4 v[122:123], v[50:53], off offset:64
	global_load_dwordx4 v[50:53], v[122:123], off offset:96
	s_waitcnt vmcnt(0)
	v_pk_fma_f32 v[50:51], v[62:63], v[66:67], v[50:51] op_sel_hi:[1,0,1]
	v_pk_fma_f32 v[52:53], v[64:65], v[66:67], v[52:53] op_sel_hi:[1,0,1]
	global_store_dwordx4 v[122:123], v[50:53], off offset:96
	global_load_dwordx4 v[50:53], v[122:123], off offset:128
	s_waitcnt vmcnt(0)
	v_pk_fma_f32 v[34:35], v[34:35], v[66:67], v[50:51] op_sel_hi:[1,0,1]
	v_pk_fma_f32 v[36:37], v[36:37], v[66:67], v[52:53] op_sel_hi:[1,0,1]
	global_store_dwordx4 v[122:123], v[34:37], off offset:128
	global_load_dwordx4 v[34:37], v[122:123], off offset:160
	s_waitcnt vmcnt(0)
	v_pk_fma_f32 v[34:35], v[38:39], v[66:67], v[34:35] op_sel_hi:[1,0,1]
	v_pk_fma_f32 v[36:37], v[40:41], v[66:67], v[36:37] op_sel_hi:[1,0,1]
	global_store_dwordx4 v[122:123], v[34:37], off offset:160
	global_load_dwordx4 v[34:37], v[122:123], off offset:192
	s_waitcnt vmcnt(0)
	v_pk_fma_f32 v[34:35], v[42:43], v[66:67], v[34:35] op_sel_hi:[1,0,1]
	v_pk_fma_f32 v[36:37], v[44:45], v[66:67], v[36:37] op_sel_hi:[1,0,1]
	global_store_dwordx4 v[122:123], v[34:37], off offset:192
	global_load_dwordx4 v[34:37], v[122:123], off offset:224
	s_waitcnt vmcnt(0)
	v_pk_fma_f32 v[34:35], v[46:47], v[66:67], v[34:35] op_sel_hi:[1,0,1]
	v_pk_fma_f32 v[36:37], v[48:49], v[66:67], v[36:37] op_sel_hi:[1,0,1]
	global_store_dwordx4 v[122:123], v[34:37], off offset:224
	global_load_dwordx4 v[34:37], v[122:123], off offset:256
	s_waitcnt vmcnt(0)
	v_pk_fma_f32 v[18:19], v[18:19], v[66:67], v[34:35] op_sel_hi:[1,0,1]
	v_pk_fma_f32 v[20:21], v[20:21], v[66:67], v[36:37] op_sel_hi:[1,0,1]
	global_store_dwordx4 v[122:123], v[18:21], off offset:256
	global_load_dwordx4 v[18:21], v[122:123], off offset:288
	s_waitcnt vmcnt(0)
	v_pk_fma_f32 v[18:19], v[22:23], v[66:67], v[18:19] op_sel_hi:[1,0,1]
	v_pk_fma_f32 v[20:21], v[24:25], v[66:67], v[20:21] op_sel_hi:[1,0,1]
	global_store_dwordx4 v[122:123], v[18:21], off offset:288
	global_load_dwordx4 v[18:21], v[122:123], off offset:320
	s_waitcnt vmcnt(0)
	v_pk_fma_f32 v[18:19], v[26:27], v[66:67], v[18:19] op_sel_hi:[1,0,1]
	v_pk_fma_f32 v[20:21], v[28:29], v[66:67], v[20:21] op_sel_hi:[1,0,1]
	global_store_dwordx4 v[122:123], v[18:21], off offset:320
	global_load_dwordx4 v[18:21], v[122:123], off offset:352
	s_waitcnt vmcnt(0)
	v_pk_fma_f32 v[18:19], v[30:31], v[66:67], v[18:19] op_sel_hi:[1,0,1]
	v_pk_fma_f32 v[20:21], v[32:33], v[66:67], v[20:21] op_sel_hi:[1,0,1]
	global_store_dwordx4 v[122:123], v[18:21], off offset:352
	global_load_dwordx4 v[18:21], v[122:123], off offset:384
	s_waitcnt vmcnt(0)
	v_pk_fma_f32 v[2:3], v[2:3], v[66:67], v[18:19] op_sel_hi:[1,0,1]
	v_pk_fma_f32 v[4:5], v[4:5], v[66:67], v[20:21] op_sel_hi:[1,0,1]
	global_store_dwordx4 v[122:123], v[2:5], off offset:384
	global_load_dwordx4 v[2:5], v[122:123], off offset:416
	s_waitcnt vmcnt(0)
	v_pk_fma_f32 v[2:3], v[6:7], v[66:67], v[2:3] op_sel_hi:[1,0,1]
	v_pk_fma_f32 v[4:5], v[8:9], v[66:67], v[4:5] op_sel_hi:[1,0,1]
	global_store_dwordx4 v[122:123], v[2:5], off offset:416
	global_load_dwordx4 v[2:5], v[122:123], off offset:448
	s_waitcnt vmcnt(0)
	v_pk_fma_f32 v[2:3], v[10:11], v[66:67], v[2:3] op_sel_hi:[1,0,1]
	v_pk_fma_f32 v[4:5], v[12:13], v[66:67], v[4:5] op_sel_hi:[1,0,1]
	global_store_dwordx4 v[122:123], v[2:5], off offset:448
	global_load_dwordx4 v[2:5], v[122:123], off offset:480
	s_waitcnt vmcnt(0)
	v_pk_fma_f32 v[2:3], v[14:15], v[66:67], v[2:3] op_sel_hi:[1,0,1]
	v_pk_fma_f32 v[4:5], v[16:17], v[66:67], v[4:5] op_sel_hi:[1,0,1]
	global_store_dwordx4 v[122:123], v[2:5], off offset:480
	v_mov_b32_e32 v16, v1
	v_mov_b32_e32 v17, v1
	v_mov_b32_e32 v2, v1
	v_mov_b32_e32 v3, v1
	v_mov_b32_e32 v4, v1
	v_mov_b32_e32 v5, v1
	v_mov_b32_e32 v6, v1
	v_mov_b32_e32 v7, v1
	v_mov_b32_e32 v8, v1
	v_mov_b32_e32 v9, v1
	v_mov_b32_e32 v10, v1
	v_mov_b32_e32 v11, v1
	v_mov_b32_e32 v12, v1
	v_mov_b32_e32 v13, v1
	v_mov_b32_e32 v14, v1
	v_mov_b32_e32 v15, v1
	v_mov_b64_e32 v[32:33], v[16:17]
	v_mov_b64_e32 v[48:49], v[16:17]
	v_mov_b64_e32 v[64:65], v[16:17]
	v_mov_b32_e32 v66, 0
	v_mov_b32_e32 v67, 0x41a00000
	v_mov_b64_e32 v[30:31], v[14:15]
	v_mov_b64_e32 v[28:29], v[12:13]
	v_mov_b64_e32 v[26:27], v[10:11]
	v_mov_b64_e32 v[24:25], v[8:9]
	v_mov_b64_e32 v[22:23], v[6:7]
	v_mov_b64_e32 v[20:21], v[4:5]
	v_mov_b64_e32 v[18:19], v[2:3]
	v_mov_b64_e32 v[46:47], v[14:15]
	v_mov_b64_e32 v[44:45], v[12:13]
	v_mov_b64_e32 v[42:43], v[10:11]
	v_mov_b64_e32 v[40:41], v[8:9]
	v_mov_b64_e32 v[38:39], v[6:7]
	v_mov_b64_e32 v[36:37], v[4:5]
	v_mov_b64_e32 v[34:35], v[2:3]
	v_mov_b64_e32 v[62:63], v[14:15]
	v_mov_b64_e32 v[60:61], v[12:13]
	v_mov_b64_e32 v[58:59], v[10:11]
	v_mov_b64_e32 v[56:57], v[8:9]
	v_mov_b64_e32 v[54:55], v[6:7]
	v_mov_b64_e32 v[52:53], v[4:5]
	v_mov_b64_e32 v[50:51], v[2:3]
